# once-read f32 weight streams (adaLN GEMV, f32->bf16 weight conversion) loaded with the nt hint
# speedup vs baseline: 1.0051x; 1.0051x over previous
.LBB0_24:
	s_mov_b64 s[18:19], s[4:5]
	s_mov_b32 s17, 3
	global_load_dword v108, v172, s[18:19] nt
	s_add_u32 s18, s18, 0xc000
	s_addc_u32 s19, s19, 0
	global_load_dword v109, v172, s[18:19] nt
	s_add_u32 s18, s18, 0xc000
	s_addc_u32 s19, s19, 0
	global_load_dword v110, v172, s[18:19] nt
	s_add_u32 s18, s18, 0xc000
	s_addc_u32 s19, s19, 0
	global_load_dword v111, v172, s[18:19] nt
	s_add_u32 s18, s18, 0xc000
	s_addc_u32 s19, s19, 0
	global_load_dword v112, v172, s[18:19] nt
	s_add_u32 s18, s18, 0xc000
	s_addc_u32 s19, s19, 0
	global_load_dword v113, v172, s[18:19] nt
	s_add_u32 s18, s18, 0xc000
	s_addc_u32 s19, s19, 0
	global_load_dword v114, v172, s[18:19] nt
	s_add_u32 s18, s18, 0xc000
	s_addc_u32 s19, s19, 0
	global_load_dword v115, v172, s[18:19] nt
	s_add_u32 s18, s18, 0xc000
	s_addc_u32 s19, s19, 0
	global_load_dword v116, v172, s[18:19] nt
	s_add_u32 s18, s18, 0xc000
	s_addc_u32 s19, s19, 0
	global_load_dword v117, v172, s[18:19] nt
	s_add_u32 s18, s18, 0xc000
	s_addc_u32 s19, s19, 0
	global_load_dword v118, v172, s[18:19] nt
	s_add_u32 s18, s18, 0xc000
	s_addc_u32 s19, s19, 0
	global_load_dword v119, v172, s[18:19] nt
	s_add_u32 s18, s18, 0xc000
	s_addc_u32 s19, s19, 0
	global_load_dword v120, v172, s[18:19] nt
	s_add_u32 s18, s18, 0xc000
	s_addc_u32 s19, s19, 0
	global_load_dword v121, v172, s[18:19] nt
	s_add_u32 s18, s18, 0xc000
	s_addc_u32 s19, s19, 0
	global_load_dword v122, v172, s[18:19] nt
	s_add_u32 s18, s18, 0xc000
	s_addc_u32 s19, s19, 0
	global_load_dword v123, v172, s[18:19] nt
	s_add_u32 s18, s18, 0xc000
	s_addc_u32 s19, s19, 0
	global_load_dword v124, v172, s[18:19] nt
	s_add_u32 s18, s18, 0xc000
	s_addc_u32 s19, s19, 0
	global_load_dword v125, v172, s[18:19] nt
	s_add_u32 s18, s18, 0xc000
	s_addc_u32 s19, s19, 0
	global_load_dword v126, v172, s[18:19] nt
	s_add_u32 s18, s18, 0xc000
	s_addc_u32 s19, s19, 0
	global_load_dword v127, v172, s[18:19] nt
	s_add_u32 s18, s18, 0xc000
	s_addc_u32 s19, s19, 0
	global_load_dword v128, v172, s[18:19] nt
	s_add_u32 s18, s18, 0xc000
	s_addc_u32 s19, s19, 0
	global_load_dword v129, v172, s[18:19] nt
	s_add_u32 s18, s18, 0xc000
	s_addc_u32 s19, s19, 0
	global_load_dword v130, v172, s[18:19] nt
	s_add_u32 s18, s18, 0xc000
	s_addc_u32 s19, s19, 0
	global_load_dword v131, v172, s[18:19] nt
	s_add_u32 s18, s18, 0xc000
	s_addc_u32 s19, s19, 0
	global_load_dword v132, v172, s[18:19] nt
	s_add_u32 s18, s18, 0xc000
	s_addc_u32 s19, s19, 0
	global_load_dword v133, v172, s[18:19] nt
	s_add_u32 s18, s18, 0xc000
	s_addc_u32 s19, s19, 0
	global_load_dword v134, v172, s[18:19] nt
	s_add_u32 s18, s18, 0xc000
	s_addc_u32 s19, s19, 0
	global_load_dword v135, v172, s[18:19] nt
	s_add_u32 s18, s18, 0xc000
	s_addc_u32 s19, s19, 0
	global_load_dword v136, v172, s[18:19] nt
	s_add_u32 s18, s18, 0xc000
	s_addc_u32 s19, s19, 0
	global_load_dword v137, v172, s[18:19] nt
	s_add_u32 s18, s18, 0xc000
	s_addc_u32 s19, s19, 0
	global_load_dword v138, v172, s[18:19] nt
	s_add_u32 s18, s18, 0xc000
	s_addc_u32 s19, s19, 0
	global_load_dword v139, v172, s[18:19] nt
	s_add_u32 s18, s18, 0xc000
	s_addc_u32 s19, s19, 0
.Lada_loop:
	global_load_dword v140, v172, s[18:19] nt
	s_add_u32 s18, s18, 0xc000
	s_addc_u32 s19, s19, 0
	global_load_dword v141, v172, s[18:19] nt
	s_add_u32 s18, s18, 0xc000
	s_addc_u32 s19, s19, 0
	global_load_dword v142, v172, s[18:19] nt
	s_add_u32 s18, s18, 0xc000
	s_addc_u32 s19, s19, 0
	global_load_dword v143, v172, s[18:19] nt
	s_add_u32 s18, s18, 0xc000
	s_addc_u32 s19, s19, 0
	global_load_dword v144, v172, s[18:19] nt
	s_add_u32 s18, s18, 0xc000
	s_addc_u32 s19, s19, 0
	global_load_dword v145, v172, s[18:19] nt
	s_add_u32 s18, s18, 0xc000
	s_addc_u32 s19, s19, 0
	global_load_dword v146, v172, s[18:19] nt
	s_add_u32 s18, s18, 0xc000
	s_addc_u32 s19, s19, 0
	global_load_dword v147, v172, s[18:19] nt
	s_add_u32 s18, s18, 0xc000
	s_addc_u32 s19, s19, 0
	global_load_dword v148, v172, s[18:19] nt
	s_add_u32 s18, s18, 0xc000
	s_addc_u32 s19, s19, 0
	global_load_dword v149, v172, s[18:19] nt
	s_add_u32 s18, s18, 0xc000
	s_addc_u32 s19, s19, 0
	global_load_dword v150, v172, s[18:19] nt
	s_add_u32 s18, s18, 0xc000
	s_addc_u32 s19, s19, 0
	global_load_dword v151, v172, s[18:19] nt
	s_add_u32 s18, s18, 0xc000
	s_addc_u32 s19, s19, 0
	global_load_dword v152, v172, s[18:19] nt
	s_add_u32 s18, s18, 0xc000
	s_addc_u32 s19, s19, 0
	global_load_dword v153, v172, s[18:19] nt
	s_add_u32 s18, s18, 0xc000
	s_addc_u32 s19, s19, 0
	global_load_dword v154, v172, s[18:19] nt
	s_add_u32 s18, s18, 0xc000
	s_addc_u32 s19, s19, 0
	global_load_dword v155, v172, s[18:19] nt
	s_add_u32 s18, s18, 0xc000
	s_addc_u32 s19, s19, 0
	global_load_dword v156, v172, s[18:19] nt
	s_add_u32 s18, s18, 0xc000
	s_addc_u32 s19, s19, 0
	global_load_dword v157, v172, s[18:19] nt
	s_add_u32 s18, s18, 0xc000
	s_addc_u32 s19, s19, 0
	global_load_dword v158, v172, s[18:19] nt
	s_add_u32 s18, s18, 0xc000
	s_addc_u32 s19, s19, 0
	global_load_dword v159, v172, s[18:19] nt
	s_add_u32 s18, s18, 0xc000
	s_addc_u32 s19, s19, 0
	global_load_dword v160, v172, s[18:19] nt
	s_add_u32 s18, s18, 0xc000
	s_addc_u32 s19, s19, 0
	global_load_dword v161, v172, s[18:19] nt
	s_add_u32 s18, s18, 0xc000
	s_addc_u32 s19, s19, 0
	global_load_dword v162, v172, s[18:19] nt
	s_add_u32 s18, s18, 0xc000
	s_addc_u32 s19, s19, 0
	global_load_dword v163, v172, s[18:19] nt
	s_add_u32 s18, s18, 0xc000
	s_addc_u32 s19, s19, 0
	global_load_dword v164, v172, s[18:19] nt
	s_add_u32 s18, s18, 0xc000
	s_addc_u32 s19, s19, 0
	global_load_dword v165, v172, s[18:19] nt
	s_add_u32 s18, s18, 0xc000
	s_addc_u32 s19, s19, 0
	global_load_dword v166, v172, s[18:19] nt
	s_add_u32 s18, s18, 0xc000
	s_addc_u32 s19, s19, 0
	global_load_dword v167, v172, s[18:19] nt
	s_add_u32 s18, s18, 0xc000
	s_addc_u32 s19, s19, 0
	global_load_dword v168, v172, s[18:19] nt
	s_add_u32 s18, s18, 0xc000
	s_addc_u32 s19, s19, 0
	global_load_dword v169, v172, s[18:19] nt
	s_add_u32 s18, s18, 0xc000
	s_addc_u32 s19, s19, 0
	global_load_dword v170, v172, s[18:19] nt
	s_add_u32 s18, s18, 0xc000
	s_addc_u32 s19, s19, 0
	global_load_dword v171, v172, s[18:19] nt
	s_add_u32 s18, s18, 0xc000
	s_addc_u32 s19, s19, 0
	v_mov_b32_e32 v173, s15
	ds_read_b128 v[12:15], v173 offset:0
	ds_read_b128 v[16:19], v173 offset:16
	ds_read_b128 v[20:23], v173 offset:32
	ds_read_b128 v[24:27], v173 offset:48
	ds_read_b128 v[28:31], v173 offset:64
	ds_read_b128 v[32:35], v173 offset:80
	ds_read_b128 v[36:39], v173 offset:96
	ds_read_b128 v[40:43], v173 offset:112
	ds_read_b128 v[44:47], v173 offset:8192
	ds_read_b128 v[48:51], v173 offset:8208
	ds_read_b128 v[52:55], v173 offset:8224
	ds_read_b128 v[56:59], v173 offset:8240
	ds_read_b128 v[60:63], v173 offset:8256
	ds_read_b128 v[64:67], v173 offset:8272
	ds_read_b128 v[68:71], v173 offset:8288
	ds_read_b128 v[72:75], v173 offset:8304
	ds_read_b128 v[76:79], v173 offset:16384
	ds_read_b128 v[80:83], v173 offset:16400
	ds_read_b128 v[84:87], v173 offset:16416
	ds_read_b128 v[88:91], v173 offset:16432
	ds_read_b128 v[92:95], v173 offset:16448
	ds_read_b128 v[96:99], v173 offset:16464
	ds_read_b128 v[100:103], v173 offset:16480
	ds_read_b128 v[104:107], v173 offset:16496
	s_addk_i32 s15, 0x80
	s_waitcnt lgkmcnt(0)
	s_waitcnt vmcnt(63)
	v_fmac_f32_e32 v10, v108, v12
	v_fmac_f32_e32 v11, v108, v44
	v_fmac_f32_e32 v7, v108, v76
	s_waitcnt vmcnt(62)
	v_fmac_f32_e32 v10, v109, v13
	v_fmac_f32_e32 v11, v109, v45
	v_fmac_f32_e32 v7, v109, v77
	s_waitcnt vmcnt(61)
	v_fmac_f32_e32 v10, v110, v14
	v_fmac_f32_e32 v11, v110, v46
	v_fmac_f32_e32 v7, v110, v78
	s_waitcnt vmcnt(60)
	v_fmac_f32_e32 v10, v111, v15
	v_fmac_f32_e32 v11, v111, v47
	v_fmac_f32_e32 v7, v111, v79
	s_waitcnt vmcnt(59)
	v_fmac_f32_e32 v10, v112, v16
	v_fmac_f32_e32 v11, v112, v48
	v_fmac_f32_e32 v7, v112, v80
	s_waitcnt vmcnt(58)
	v_fmac_f32_e32 v10, v113, v17
	v_fmac_f32_e32 v11, v113, v49
	v_fmac_f32_e32 v7, v113, v81
	s_waitcnt vmcnt(57)
	v_fmac_f32_e32 v10, v114, v18
	v_fmac_f32_e32 v11, v114, v50
	v_fmac_f32_e32 v7, v114, v82
	s_waitcnt vmcnt(56)
	v_fmac_f32_e32 v10, v115, v19
	v_fmac_f32_e32 v11, v115, v51
	v_fmac_f32_e32 v7, v115, v83
	s_waitcnt vmcnt(55)
	v_fmac_f32_e32 v10, v116, v20
	v_fmac_f32_e32 v11, v116, v52
	v_fmac_f32_e32 v7, v116, v84
	s_waitcnt vmcnt(54)
	v_fmac_f32_e32 v10, v117, v21
	v_fmac_f32_e32 v11, v117, v53
	v_fmac_f32_e32 v7, v117, v85
	s_waitcnt vmcnt(53)
	v_fmac_f32_e32 v10, v118, v22
	v_fmac_f32_e32 v11, v118, v54
	v_fmac_f32_e32 v7, v118, v86
	s_waitcnt vmcnt(52)
	v_fmac_f32_e32 v10, v119, v23
	v_fmac_f32_e32 v11, v119, v55
	v_fmac_f32_e32 v7, v119, v87
	s_waitcnt vmcnt(51)
	v_fmac_f32_e32 v10, v120, v24
	v_fmac_f32_e32 v11, v120, v56
	v_fmac_f32_e32 v7, v120, v88
	s_waitcnt vmcnt(50)
	v_fmac_f32_e32 v10, v121, v25
	v_fmac_f32_e32 v11, v121, v57
	v_fmac_f32_e32 v7, v121, v89
	s_waitcnt vmcnt(49)
	v_fmac_f32_e32 v10, v122, v26
	v_fmac_f32_e32 v11, v122, v58
	v_fmac_f32_e32 v7, v122, v90
	s_waitcnt vmcnt(48)
	v_fmac_f32_e32 v10, v123, v27
	v_fmac_f32_e32 v11, v123, v59
	v_fmac_f32_e32 v7, v123, v91
	s_waitcnt vmcnt(47)
	v_fmac_f32_e32 v10, v124, v28
	v_fmac_f32_e32 v11, v124, v60
	v_fmac_f32_e32 v7, v124, v92
	s_waitcnt vmcnt(46)
	v_fmac_f32_e32 v10, v125, v29
	v_fmac_f32_e32 v11, v125, v61
	v_fmac_f32_e32 v7, v125, v93
	s_waitcnt vmcnt(45)
	v_fmac_f32_e32 v10, v126, v30
	v_fmac_f32_e32 v11, v126, v62
	v_fmac_f32_e32 v7, v126, v94
	s_waitcnt vmcnt(44)
	v_fmac_f32_e32 v10, v127, v31
	v_fmac_f32_e32 v11, v127, v63
	v_fmac_f32_e32 v7, v127, v95
	s_waitcnt vmcnt(43)
	v_fmac_f32_e32 v10, v128, v32
	v_fmac_f32_e32 v11, v128, v64
	v_fmac_f32_e32 v7, v128, v96
	s_waitcnt vmcnt(42)
	v_fmac_f32_e32 v10, v129, v33
	v_fmac_f32_e32 v11, v129, v65
	v_fmac_f32_e32 v7, v129, v97
	s_waitcnt vmcnt(41)
	v_fmac_f32_e32 v10, v130, v34
	v_fmac_f32_e32 v11, v130, v66
	v_fmac_f32_e32 v7, v130, v98
	s_waitcnt vmcnt(40)
	v_fmac_f32_e32 v10, v131, v35
	v_fmac_f32_e32 v11, v131, v67
	v_fmac_f32_e32 v7, v131, v99
	s_waitcnt vmcnt(39)
	v_fmac_f32_e32 v10, v132, v36
	v_fmac_f32_e32 v11, v132, v68
	v_fmac_f32_e32 v7, v132, v100
	s_waitcnt vmcnt(38)
	v_fmac_f32_e32 v10, v133, v37
	v_fmac_f32_e32 v11, v133, v69
	v_fmac_f32_e32 v7, v133, v101
	s_waitcnt vmcnt(37)
	v_fmac_f32_e32 v10, v134, v38
	v_fmac_f32_e32 v11, v134, v70
	v_fmac_f32_e32 v7, v134, v102
	s_waitcnt vmcnt(36)
	v_fmac_f32_e32 v10, v135, v39
	v_fmac_f32_e32 v11, v135, v71
	v_fmac_f32_e32 v7, v135, v103
	s_waitcnt vmcnt(35)
	v_fmac_f32_e32 v10, v136, v40
	v_fmac_f32_e32 v11, v136, v72
	v_fmac_f32_e32 v7, v136, v104
	s_waitcnt vmcnt(34)
	v_fmac_f32_e32 v10, v137, v41
	v_fmac_f32_e32 v11, v137, v73
	v_fmac_f32_e32 v7, v137, v105
	s_waitcnt vmcnt(33)
	v_fmac_f32_e32 v10, v138, v42
	v_fmac_f32_e32 v11, v138, v74
	v_fmac_f32_e32 v7, v138, v106
	s_waitcnt vmcnt(32)
	v_fmac_f32_e32 v10, v139, v43
	v_fmac_f32_e32 v11, v139, v75
	v_fmac_f32_e32 v7, v139, v107
	global_load_dword v108, v172, s[18:19] nt
	s_add_u32 s18, s18, 0xc000
	s_addc_u32 s19, s19, 0
	global_load_dword v109, v172, s[18:19] nt
	s_add_u32 s18, s18, 0xc000
	s_addc_u32 s19, s19, 0
	global_load_dword v110, v172, s[18:19] nt
	s_add_u32 s18, s18, 0xc000
	s_addc_u32 s19, s19, 0
	global_load_dword v111, v172, s[18:19] nt
	s_add_u32 s18, s18, 0xc000
	s_addc_u32 s19, s19, 0
	global_load_dword v112, v172, s[18:19] nt
	s_add_u32 s18, s18, 0xc000
	s_addc_u32 s19, s19, 0
	global_load_dword v113, v172, s[18:19] nt
	s_add_u32 s18, s18, 0xc000
	s_addc_u32 s19, s19, 0
	global_load_dword v114, v172, s[18:19] nt
	s_add_u32 s18, s18, 0xc000
	s_addc_u32 s19, s19, 0
	global_load_dword v115, v172, s[18:19] nt
	s_add_u32 s18, s18, 0xc000
	s_addc_u32 s19, s19, 0
	global_load_dword v116, v172, s[18:19] nt
	s_add_u32 s18, s18, 0xc000
	s_addc_u32 s19, s19, 0
	global_load_dword v117, v172, s[18:19] nt
	s_add_u32 s18, s18, 0xc000
	s_addc_u32 s19, s19, 0
	global_load_dword v118, v172, s[18:19] nt
	s_add_u32 s18, s18, 0xc000
	s_addc_u32 s19, s19, 0
	global_load_dword v119, v172, s[18:19] nt
	s_add_u32 s18, s18, 0xc000
	s_addc_u32 s19, s19, 0
	global_load_dword v120, v172, s[18:19] nt
	s_add_u32 s18, s18, 0xc000
	s_addc_u32 s19, s19, 0
	global_load_dword v121, v172, s[18:19] nt
	s_add_u32 s18, s18, 0xc000
	s_addc_u32 s19, s19, 0
	global_load_dword v122, v172, s[18:19] nt
	s_add_u32 s18, s18, 0xc000
	s_addc_u32 s19, s19, 0
	global_load_dword v123, v172, s[18:19] nt
	s_add_u32 s18, s18, 0xc000
	s_addc_u32 s19, s19, 0
	global_load_dword v124, v172, s[18:19] nt
	s_add_u32 s18, s18, 0xc000
	s_addc_u32 s19, s19, 0
	global_load_dword v125, v172, s[18:19] nt
	s_add_u32 s18, s18, 0xc000
	s_addc_u32 s19, s19, 0
	global_load_dword v126, v172, s[18:19] nt
	s_add_u32 s18, s18, 0xc000
	s_addc_u32 s19, s19, 0
	global_load_dword v127, v172, s[18:19] nt
	s_add_u32 s18, s18, 0xc000
	s_addc_u32 s19, s19, 0
	global_load_dword v128, v172, s[18:19] nt
	s_add_u32 s18, s18, 0xc000
	s_addc_u32 s19, s19, 0
	global_load_dword v129, v172, s[18:19] nt
	s_add_u32 s18, s18, 0xc000
	s_addc_u32 s19, s19, 0
	global_load_dword v130, v172, s[18:19] nt
	s_add_u32 s18, s18, 0xc000
	s_addc_u32 s19, s19, 0
	global_load_dword v131, v172, s[18:19] nt
	s_add_u32 s18, s18, 0xc000
	s_addc_u32 s19, s19, 0
	global_load_dword v132, v172, s[18:19] nt
	s_add_u32 s18, s18, 0xc000
	s_addc_u32 s19, s19, 0
	global_load_dword v133, v172, s[18:19] nt
	s_add_u32 s18, s18, 0xc000
	s_addc_u32 s19, s19, 0
	global_load_dword v134, v172, s[18:19] nt
	s_add_u32 s18, s18, 0xc000
	s_addc_u32 s19, s19, 0
	global_load_dword v135, v172, s[18:19] nt
	s_add_u32 s18, s18, 0xc000
	s_addc_u32 s19, s19, 0
	global_load_dword v136, v172, s[18:19] nt
	s_add_u32 s18, s18, 0xc000
	s_addc_u32 s19, s19, 0
	global_load_dword v137, v172, s[18:19] nt
	s_add_u32 s18, s18, 0xc000
	s_addc_u32 s19, s19, 0
	global_load_dword v138, v172, s[18:19] nt
	s_add_u32 s18, s18, 0xc000
	s_addc_u32 s19, s19, 0
	global_load_dword v139, v172, s[18:19] nt
	s_add_u32 s18, s18, 0xc000
	s_addc_u32 s19, s19, 0
	v_mov_b32_e32 v173, s15
	ds_read_b128 v[12:15], v173 offset:0
	ds_read_b128 v[16:19], v173 offset:16
	ds_read_b128 v[20:23], v173 offset:32
	ds_read_b128 v[24:27], v173 offset:48
	ds_read_b128 v[28:31], v173 offset:64
	ds_read_b128 v[32:35], v173 offset:80
	ds_read_b128 v[36:39], v173 offset:96
	ds_read_b128 v[40:43], v173 offset:112
	ds_read_b128 v[44:47], v173 offset:8192
	ds_read_b128 v[48:51], v173 offset:8208
	ds_read_b128 v[52:55], v173 offset:8224
	ds_read_b128 v[56:59], v173 offset:8240
	ds_read_b128 v[60:63], v173 offset:8256
	ds_read_b128 v[64:67], v173 offset:8272
	ds_read_b128 v[68:71], v173 offset:8288
	ds_read_b128 v[72:75], v173 offset:8304
	ds_read_b128 v[76:79], v173 offset:16384
	ds_read_b128 v[80:83], v173 offset:16400
	ds_read_b128 v[84:87], v173 offset:16416
	ds_read_b128 v[88:91], v173 offset:16432
	ds_read_b128 v[92:95], v173 offset:16448
	ds_read_b128 v[96:99], v173 offset:16464
	ds_read_b128 v[100:103], v173 offset:16480
	ds_read_b128 v[104:107], v173 offset:16496
	s_addk_i32 s15, 0x80
	s_waitcnt lgkmcnt(0)
	s_waitcnt vmcnt(63)
	v_fmac_f32_e32 v10, v140, v12
	v_fmac_f32_e32 v11, v140, v44
	v_fmac_f32_e32 v7, v140, v76
	s_waitcnt vmcnt(62)
	v_fmac_f32_e32 v10, v141, v13
	v_fmac_f32_e32 v11, v141, v45
	v_fmac_f32_e32 v7, v141, v77
	s_waitcnt vmcnt(61)
	v_fmac_f32_e32 v10, v142, v14
	v_fmac_f32_e32 v11, v142, v46
	v_fmac_f32_e32 v7, v142, v78
	s_waitcnt vmcnt(60)
	v_fmac_f32_e32 v10, v143, v15
	v_fmac_f32_e32 v11, v143, v47
	v_fmac_f32_e32 v7, v143, v79
	s_waitcnt vmcnt(59)
	v_fmac_f32_e32 v10, v144, v16
	v_fmac_f32_e32 v11, v144, v48
	v_fmac_f32_e32 v7, v144, v80
	s_waitcnt vmcnt(58)
	v_fmac_f32_e32 v10, v145, v17
	v_fmac_f32_e32 v11, v145, v49
	v_fmac_f32_e32 v7, v145, v81
	s_waitcnt vmcnt(57)
	v_fmac_f32_e32 v10, v146, v18
	v_fmac_f32_e32 v11, v146, v50
	v_fmac_f32_e32 v7, v146, v82
	s_waitcnt vmcnt(56)
	v_fmac_f32_e32 v10, v147, v19
	v_fmac_f32_e32 v11, v147, v51
	v_fmac_f32_e32 v7, v147, v83
	s_waitcnt vmcnt(55)
	v_fmac_f32_e32 v10, v148, v20
	v_fmac_f32_e32 v11, v148, v52
	v_fmac_f32_e32 v7, v148, v84
	s_waitcnt vmcnt(54)
	v_fmac_f32_e32 v10, v149, v21
	v_fmac_f32_e32 v11, v149, v53
	v_fmac_f32_e32 v7, v149, v85
	s_waitcnt vmcnt(53)
	v_fmac_f32_e32 v10, v150, v22
	v_fmac_f32_e32 v11, v150, v54
	v_fmac_f32_e32 v7, v150, v86
	s_waitcnt vmcnt(52)
	v_fmac_f32_e32 v10, v151, v23
	v_fmac_f32_e32 v11, v151, v55
	v_fmac_f32_e32 v7, v151, v87
	s_waitcnt vmcnt(51)
	v_fmac_f32_e32 v10, v152, v24
	v_fmac_f32_e32 v11, v152, v56
	v_fmac_f32_e32 v7, v152, v88
	s_waitcnt vmcnt(50)
	v_fmac_f32_e32 v10, v153, v25
	v_fmac_f32_e32 v11, v153, v57
	v_fmac_f32_e32 v7, v153, v89
	s_waitcnt vmcnt(49)
	v_fmac_f32_e32 v10, v154, v26
	v_fmac_f32_e32 v11, v154, v58
	v_fmac_f32_e32 v7, v154, v90
	s_waitcnt vmcnt(48)
	v_fmac_f32_e32 v10, v155, v27
	v_fmac_f32_e32 v11, v155, v59
	v_fmac_f32_e32 v7, v155, v91
	s_waitcnt vmcnt(47)
	v_fmac_f32_e32 v10, v156, v28
	v_fmac_f32_e32 v11, v156, v60
	v_fmac_f32_e32 v7, v156, v92
	s_waitcnt vmcnt(46)
	v_fmac_f32_e32 v10, v157, v29
	v_fmac_f32_e32 v11, v157, v61
	v_fmac_f32_e32 v7, v157, v93
	s_waitcnt vmcnt(45)
	v_fmac_f32_e32 v10, v158, v30
	v_fmac_f32_e32 v11, v158, v62
	v_fmac_f32_e32 v7, v158, v94
	s_waitcnt vmcnt(44)
	v_fmac_f32_e32 v10, v159, v31
	v_fmac_f32_e32 v11, v159, v63
	v_fmac_f32_e32 v7, v159, v95
	s_waitcnt vmcnt(43)
	v_fmac_f32_e32 v10, v160, v32
	v_fmac_f32_e32 v11, v160, v64
	v_fmac_f32_e32 v7, v160, v96
	s_waitcnt vmcnt(42)
	v_fmac_f32_e32 v10, v161, v33
	v_fmac_f32_e32 v11, v161, v65
	v_fmac_f32_e32 v7, v161, v97
	s_waitcnt vmcnt(41)
	v_fmac_f32_e32 v10, v162, v34
	v_fmac_f32_e32 v11, v162, v66
	v_fmac_f32_e32 v7, v162, v98
	s_waitcnt vmcnt(40)
	v_fmac_f32_e32 v10, v163, v35
	v_fmac_f32_e32 v11, v163, v67
	v_fmac_f32_e32 v7, v163, v99
	s_waitcnt vmcnt(39)
	v_fmac_f32_e32 v10, v164, v36
	v_fmac_f32_e32 v11, v164, v68
	v_fmac_f32_e32 v7, v164, v100
	s_waitcnt vmcnt(38)
	v_fmac_f32_e32 v10, v165, v37
	v_fmac_f32_e32 v11, v165, v69
	v_fmac_f32_e32 v7, v165, v101
	s_waitcnt vmcnt(37)
	v_fmac_f32_e32 v10, v166, v38
	v_fmac_f32_e32 v11, v166, v70
	v_fmac_f32_e32 v7, v166, v102
	s_waitcnt vmcnt(36)
	v_fmac_f32_e32 v10, v167, v39
	v_fmac_f32_e32 v11, v167, v71
	v_fmac_f32_e32 v7, v167, v103
	s_waitcnt vmcnt(35)
	v_fmac_f32_e32 v10, v168, v40
	v_fmac_f32_e32 v11, v168, v72
	v_fmac_f32_e32 v7, v168, v104
	s_waitcnt vmcnt(34)
	v_fmac_f32_e32 v10, v169, v41
	v_fmac_f32_e32 v11, v169, v73
	v_fmac_f32_e32 v7, v169, v105
	s_waitcnt vmcnt(33)
	v_fmac_f32_e32 v10, v170, v42
	v_fmac_f32_e32 v11, v170, v74
	v_fmac_f32_e32 v7, v170, v106
	s_waitcnt vmcnt(32)
	v_fmac_f32_e32 v10, v171, v43
	v_fmac_f32_e32 v11, v171, v75
	v_fmac_f32_e32 v7, v171, v107
	s_sub_u32 s17, s17, 1
	s_cmp_lg_u32 s17, 0
	s_cbranch_scc1 .Lada_loop
	global_load_dword v140, v172, s[18:19] nt
	s_add_u32 s18, s18, 0xc000
	s_addc_u32 s19, s19, 0
	global_load_dword v141, v172, s[18:19] nt
	s_add_u32 s18, s18, 0xc000
	s_addc_u32 s19, s19, 0
	global_load_dword v142, v172, s[18:19] nt
	s_add_u32 s18, s18, 0xc000
	s_addc_u32 s19, s19, 0
	global_load_dword v143, v172, s[18:19] nt
	s_add_u32 s18, s18, 0xc000
	s_addc_u32 s19, s19, 0
	global_load_dword v144, v172, s[18:19] nt
	s_add_u32 s18, s18, 0xc000
	s_addc_u32 s19, s19, 0
	global_load_dword v145, v172, s[18:19] nt
	s_add_u32 s18, s18, 0xc000
	s_addc_u32 s19, s19, 0
	global_load_dword v146, v172, s[18:19] nt
	s_add_u32 s18, s18, 0xc000
	s_addc_u32 s19, s19, 0
	global_load_dword v147, v172, s[18:19] nt
	s_add_u32 s18, s18, 0xc000
	s_addc_u32 s19, s19, 0
	global_load_dword v148, v172, s[18:19] nt
	s_add_u32 s18, s18, 0xc000
	s_addc_u32 s19, s19, 0
	global_load_dword v149, v172, s[18:19] nt
	s_add_u32 s18, s18, 0xc000
	s_addc_u32 s19, s19, 0
	global_load_dword v150, v172, s[18:19] nt
	s_add_u32 s18, s18, 0xc000
	s_addc_u32 s19, s19, 0
	global_load_dword v151, v172, s[18:19] nt
	s_add_u32 s18, s18, 0xc000
	s_addc_u32 s19, s19, 0
	global_load_dword v152, v172, s[18:19] nt
	s_add_u32 s18, s18, 0xc000
	s_addc_u32 s19, s19, 0
	global_load_dword v153, v172, s[18:19] nt
	s_add_u32 s18, s18, 0xc000
	s_addc_u32 s19, s19, 0
	global_load_dword v154, v172, s[18:19] nt
	s_add_u32 s18, s18, 0xc000
	s_addc_u32 s19, s19, 0
	global_load_dword v155, v172, s[18:19] nt
	s_add_u32 s18, s18, 0xc000
	s_addc_u32 s19, s19, 0
	global_load_dword v156, v172, s[18:19] nt
	s_add_u32 s18, s18, 0xc000
	s_addc_u32 s19, s19, 0
	global_load_dword v157, v172, s[18:19] nt
	s_add_u32 s18, s18, 0xc000
	s_addc_u32 s19, s19, 0
	global_load_dword v158, v172, s[18:19] nt
	s_add_u32 s18, s18, 0xc000
	s_addc_u32 s19, s19, 0
	global_load_dword v159, v172, s[18:19] nt
	s_add_u32 s18, s18, 0xc000
	s_addc_u32 s19, s19, 0
	global_load_dword v160, v172, s[18:19] nt
	s_add_u32 s18, s18, 0xc000
	s_addc_u32 s19, s19, 0
	global_load_dword v161, v172, s[18:19] nt
	s_add_u32 s18, s18, 0xc000
	s_addc_u32 s19, s19, 0
	global_load_dword v162, v172, s[18:19] nt
	s_add_u32 s18, s18, 0xc000
	s_addc_u32 s19, s19, 0
	global_load_dword v163, v172, s[18:19] nt
	s_add_u32 s18, s18, 0xc000
	s_addc_u32 s19, s19, 0
	global_load_dword v164, v172, s[18:19] nt
	s_add_u32 s18, s18, 0xc000
	s_addc_u32 s19, s19, 0
	global_load_dword v165, v172, s[18:19] nt
	s_add_u32 s18, s18, 0xc000
	s_addc_u32 s19, s19, 0
	global_load_dword v166, v172, s[18:19] nt
	s_add_u32 s18, s18, 0xc000
	s_addc_u32 s19, s19, 0
	global_load_dword v167, v172, s[18:19] nt
	s_add_u32 s18, s18, 0xc000
	s_addc_u32 s19, s19, 0
	global_load_dword v168, v172, s[18:19] nt
	s_add_u32 s18, s18, 0xc000
	s_addc_u32 s19, s19, 0
	global_load_dword v169, v172, s[18:19] nt
	s_add_u32 s18, s18, 0xc000
	s_addc_u32 s19, s19, 0
	global_load_dword v170, v172, s[18:19] nt
	s_add_u32 s18, s18, 0xc000
	s_addc_u32 s19, s19, 0
	global_load_dword v171, v172, s[18:19] nt
	s_add_u32 s18, s18, 0xc000
	s_addc_u32 s19, s19, 0
	v_mov_b32_e32 v173, s15
	ds_read_b128 v[12:15], v173 offset:0
	ds_read_b128 v[16:19], v173 offset:16
	ds_read_b128 v[20:23], v173 offset:32
	ds_read_b128 v[24:27], v173 offset:48
	ds_read_b128 v[28:31], v173 offset:64
	ds_read_b128 v[32:35], v173 offset:80
	ds_read_b128 v[36:39], v173 offset:96
	ds_read_b128 v[40:43], v173 offset:112
	ds_read_b128 v[44:47], v173 offset:8192
	ds_read_b128 v[48:51], v173 offset:8208
	ds_read_b128 v[52:55], v173 offset:8224
	ds_read_b128 v[56:59], v173 offset:8240
	ds_read_b128 v[60:63], v173 offset:8256
	ds_read_b128 v[64:67], v173 offset:8272
	ds_read_b128 v[68:71], v173 offset:8288
	ds_read_b128 v[72:75], v173 offset:8304
	ds_read_b128 v[76:79], v173 offset:16384
	ds_read_b128 v[80:83], v173 offset:16400
	ds_read_b128 v[84:87], v173 offset:16416
	ds_read_b128 v[88:91], v173 offset:16432
	ds_read_b128 v[92:95], v173 offset:16448
	ds_read_b128 v[96:99], v173 offset:16464
	ds_read_b128 v[100:103], v173 offset:16480
	ds_read_b128 v[104:107], v173 offset:16496
	s_addk_i32 s15, 0x80
	s_waitcnt lgkmcnt(0)
	s_waitcnt vmcnt(63)
	v_fmac_f32_e32 v10, v108, v12
	v_fmac_f32_e32 v11, v108, v44
	v_fmac_f32_e32 v7, v108, v76
	s_waitcnt vmcnt(62)
	v_fmac_f32_e32 v10, v109, v13
	v_fmac_f32_e32 v11, v109, v45
	v_fmac_f32_e32 v7, v109, v77
	s_waitcnt vmcnt(61)
	v_fmac_f32_e32 v10, v110, v14
	v_fmac_f32_e32 v11, v110, v46
	v_fmac_f32_e32 v7, v110, v78
	s_waitcnt vmcnt(60)
	v_fmac_f32_e32 v10, v111, v15
	v_fmac_f32_e32 v11, v111, v47
	v_fmac_f32_e32 v7, v111, v79
	s_waitcnt vmcnt(59)
	v_fmac_f32_e32 v10, v112, v16
	v_fmac_f32_e32 v11, v112, v48
	v_fmac_f32_e32 v7, v112, v80
	s_waitcnt vmcnt(58)
	v_fmac_f32_e32 v10, v113, v17
	v_fmac_f32_e32 v11, v113, v49
	v_fmac_f32_e32 v7, v113, v81
	s_waitcnt vmcnt(57)
	v_fmac_f32_e32 v10, v114, v18
	v_fmac_f32_e32 v11, v114, v50
	v_fmac_f32_e32 v7, v114, v82
	s_waitcnt vmcnt(56)
	v_fmac_f32_e32 v10, v115, v19
	v_fmac_f32_e32 v11, v115, v51
	v_fmac_f32_e32 v7, v115, v83
	s_waitcnt vmcnt(55)
	v_fmac_f32_e32 v10, v116, v20
	v_fmac_f32_e32 v11, v116, v52
	v_fmac_f32_e32 v7, v116, v84
	s_waitcnt vmcnt(54)
	v_fmac_f32_e32 v10, v117, v21
	v_fmac_f32_e32 v11, v117, v53
	v_fmac_f32_e32 v7, v117, v85
	s_waitcnt vmcnt(53)
	v_fmac_f32_e32 v10, v118, v22
	v_fmac_f32_e32 v11, v118, v54
	v_fmac_f32_e32 v7, v118, v86
	s_waitcnt vmcnt(52)
	v_fmac_f32_e32 v10, v119, v23
	v_fmac_f32_e32 v11, v119, v55
	v_fmac_f32_e32 v7, v119, v87
	s_waitcnt vmcnt(51)
	v_fmac_f32_e32 v10, v120, v24
	v_fmac_f32_e32 v11, v120, v56
	v_fmac_f32_e32 v7, v120, v88
	s_waitcnt vmcnt(50)
	v_fmac_f32_e32 v10, v121, v25
	v_fmac_f32_e32 v11, v121, v57
	v_fmac_f32_e32 v7, v121, v89
	s_waitcnt vmcnt(49)
	v_fmac_f32_e32 v10, v122, v26
	v_fmac_f32_e32 v11, v122, v58
	v_fmac_f32_e32 v7, v122, v90
	s_waitcnt vmcnt(48)
	v_fmac_f32_e32 v10, v123, v27
	v_fmac_f32_e32 v11, v123, v59
	v_fmac_f32_e32 v7, v123, v91
	s_waitcnt vmcnt(47)
	v_fmac_f32_e32 v10, v124, v28
	v_fmac_f32_e32 v11, v124, v60
	v_fmac_f32_e32 v7, v124, v92
	s_waitcnt vmcnt(46)
	v_fmac_f32_e32 v10, v125, v29
	v_fmac_f32_e32 v11, v125, v61
	v_fmac_f32_e32 v7, v125, v93
	s_waitcnt vmcnt(45)
	v_fmac_f32_e32 v10, v126, v30
	v_fmac_f32_e32 v11, v126, v62
	v_fmac_f32_e32 v7, v126, v94
	s_waitcnt vmcnt(44)
	v_fmac_f32_e32 v10, v127, v31
	v_fmac_f32_e32 v11, v127, v63
	v_fmac_f32_e32 v7, v127, v95
	s_waitcnt vmcnt(43)
	v_fmac_f32_e32 v10, v128, v32
	v_fmac_f32_e32 v11, v128, v64
	v_fmac_f32_e32 v7, v128, v96
	s_waitcnt vmcnt(42)
	v_fmac_f32_e32 v10, v129, v33
	v_fmac_f32_e32 v11, v129, v65
	v_fmac_f32_e32 v7, v129, v97
	s_waitcnt vmcnt(41)
	v_fmac_f32_e32 v10, v130, v34
	v_fmac_f32_e32 v11, v130, v66
	v_fmac_f32_e32 v7, v130, v98
	s_waitcnt vmcnt(40)
	v_fmac_f32_e32 v10, v131, v35
	v_fmac_f32_e32 v11, v131, v67
	v_fmac_f32_e32 v7, v131, v99
	s_waitcnt vmcnt(39)
	v_fmac_f32_e32 v10, v132, v36
	v_fmac_f32_e32 v11, v132, v68
	v_fmac_f32_e32 v7, v132, v100
	s_waitcnt vmcnt(38)
	v_fmac_f32_e32 v10, v133, v37
	v_fmac_f32_e32 v11, v133, v69
	v_fmac_f32_e32 v7, v133, v101
	s_waitcnt vmcnt(37)
	v_fmac_f32_e32 v10, v134, v38
	v_fmac_f32_e32 v11, v134, v70
	v_fmac_f32_e32 v7, v134, v102
	s_waitcnt vmcnt(36)
	v_fmac_f32_e32 v10, v135, v39
	v_fmac_f32_e32 v11, v135, v71
	v_fmac_f32_e32 v7, v135, v103
	s_waitcnt vmcnt(35)
	v_fmac_f32_e32 v10, v136, v40
	v_fmac_f32_e32 v11, v136, v72
	v_fmac_f32_e32 v7, v136, v104
	s_waitcnt vmcnt(34)
	v_fmac_f32_e32 v10, v137, v41
	v_fmac_f32_e32 v11, v137, v73
	v_fmac_f32_e32 v7, v137, v105
	s_waitcnt vmcnt(33)
	v_fmac_f32_e32 v10, v138, v42
	v_fmac_f32_e32 v11, v138, v74
	v_fmac_f32_e32 v7, v138, v106
	s_waitcnt vmcnt(32)
	v_fmac_f32_e32 v10, v139, v43
	v_fmac_f32_e32 v11, v139, v75
	v_fmac_f32_e32 v7, v139, v107
	v_mov_b32_e32 v173, s15
	ds_read_b128 v[12:15], v173 offset:0
	ds_read_b128 v[16:19], v173 offset:16
	ds_read_b128 v[20:23], v173 offset:32
	ds_read_b128 v[24:27], v173 offset:48
	ds_read_b128 v[28:31], v173 offset:64
	ds_read_b128 v[32:35], v173 offset:80
	ds_read_b128 v[36:39], v173 offset:96
	ds_read_b128 v[40:43], v173 offset:112
	ds_read_b128 v[44:47], v173 offset:8192
	ds_read_b128 v[48:51], v173 offset:8208
	ds_read_b128 v[52:55], v173 offset:8224
	ds_read_b128 v[56:59], v173 offset:8240
	ds_read_b128 v[60:63], v173 offset:8256
	ds_read_b128 v[64:67], v173 offset:8272
	ds_read_b128 v[68:71], v173 offset:8288
	ds_read_b128 v[72:75], v173 offset:8304
	ds_read_b128 v[76:79], v173 offset:16384
	ds_read_b128 v[80:83], v173 offset:16400
	ds_read_b128 v[84:87], v173 offset:16416
	ds_read_b128 v[88:91], v173 offset:16432
	ds_read_b128 v[92:95], v173 offset:16448
	ds_read_b128 v[96:99], v173 offset:16464
	ds_read_b128 v[100:103], v173 offset:16480
	ds_read_b128 v[104:107], v173 offset:16496
	s_addk_i32 s15, 0x80
	s_waitcnt lgkmcnt(0)
	s_waitcnt vmcnt(31)
	v_fmac_f32_e32 v10, v140, v12
	v_fmac_f32_e32 v11, v140, v44
	v_fmac_f32_e32 v7, v140, v76
	s_waitcnt vmcnt(30)
	v_fmac_f32_e32 v10, v141, v13
	v_fmac_f32_e32 v11, v141, v45
	v_fmac_f32_e32 v7, v141, v77
	s_waitcnt vmcnt(29)
	v_fmac_f32_e32 v10, v142, v14
	v_fmac_f32_e32 v11, v142, v46
	v_fmac_f32_e32 v7, v142, v78
	s_waitcnt vmcnt(28)
	v_fmac_f32_e32 v10, v143, v15
	v_fmac_f32_e32 v11, v143, v47
	v_fmac_f32_e32 v7, v143, v79
	s_waitcnt vmcnt(27)
	v_fmac_f32_e32 v10, v144, v16
	v_fmac_f32_e32 v11, v144, v48
	v_fmac_f32_e32 v7, v144, v80
	s_waitcnt vmcnt(26)
	v_fmac_f32_e32 v10, v145, v17
	v_fmac_f32_e32 v11, v145, v49
	v_fmac_f32_e32 v7, v145, v81
	s_waitcnt vmcnt(25)
	v_fmac_f32_e32 v10, v146, v18
	v_fmac_f32_e32 v11, v146, v50
	v_fmac_f32_e32 v7, v146, v82
	s_waitcnt vmcnt(24)
	v_fmac_f32_e32 v10, v147, v19
	v_fmac_f32_e32 v11, v147, v51
	v_fmac_f32_e32 v7, v147, v83
	s_waitcnt vmcnt(23)
	v_fmac_f32_e32 v10, v148, v20
	v_fmac_f32_e32 v11, v148, v52
	v_fmac_f32_e32 v7, v148, v84
	s_waitcnt vmcnt(22)
	v_fmac_f32_e32 v10, v149, v21
	v_fmac_f32_e32 v11, v149, v53
	v_fmac_f32_e32 v7, v149, v85
	s_waitcnt vmcnt(21)
	v_fmac_f32_e32 v10, v150, v22
	v_fmac_f32_e32 v11, v150, v54
	v_fmac_f32_e32 v7, v150, v86
	s_waitcnt vmcnt(20)
	v_fmac_f32_e32 v10, v151, v23
	v_fmac_f32_e32 v11, v151, v55
	v_fmac_f32_e32 v7, v151, v87
	s_waitcnt vmcnt(19)
	v_fmac_f32_e32 v10, v152, v24
	v_fmac_f32_e32 v11, v152, v56
	v_fmac_f32_e32 v7, v152, v88
	s_waitcnt vmcnt(18)
	v_fmac_f32_e32 v10, v153, v25
	v_fmac_f32_e32 v11, v153, v57
	v_fmac_f32_e32 v7, v153, v89
	s_waitcnt vmcnt(17)
	v_fmac_f32_e32 v10, v154, v26
	v_fmac_f32_e32 v11, v154, v58
	v_fmac_f32_e32 v7, v154, v90
	s_waitcnt vmcnt(16)
	v_fmac_f32_e32 v10, v155, v27
	v_fmac_f32_e32 v11, v155, v59
	v_fmac_f32_e32 v7, v155, v91
	s_waitcnt vmcnt(15)
	v_fmac_f32_e32 v10, v156, v28
	v_fmac_f32_e32 v11, v156, v60
	v_fmac_f32_e32 v7, v156, v92
	s_waitcnt vmcnt(14)
	v_fmac_f32_e32 v10, v157, v29
	v_fmac_f32_e32 v11, v157, v61
	v_fmac_f32_e32 v7, v157, v93
	s_waitcnt vmcnt(13)
	v_fmac_f32_e32 v10, v158, v30
	v_fmac_f32_e32 v11, v158, v62
	v_fmac_f32_e32 v7, v158, v94
	s_waitcnt vmcnt(12)
	v_fmac_f32_e32 v10, v159, v31
	v_fmac_f32_e32 v11, v159, v63
	v_fmac_f32_e32 v7, v159, v95
	s_waitcnt vmcnt(11)
	v_fmac_f32_e32 v10, v160, v32
	v_fmac_f32_e32 v11, v160, v64
	v_fmac_f32_e32 v7, v160, v96
	s_waitcnt vmcnt(10)
	v_fmac_f32_e32 v10, v161, v33
	v_fmac_f32_e32 v11, v161, v65
	v_fmac_f32_e32 v7, v161, v97
	s_waitcnt vmcnt(9)
	v_fmac_f32_e32 v10, v162, v34
	v_fmac_f32_e32 v11, v162, v66
	v_fmac_f32_e32 v7, v162, v98
	s_waitcnt vmcnt(8)
	v_fmac_f32_e32 v10, v163, v35
	v_fmac_f32_e32 v11, v163, v67
	v_fmac_f32_e32 v7, v163, v99
	s_waitcnt vmcnt(7)
	v_fmac_f32_e32 v10, v164, v36
	v_fmac_f32_e32 v11, v164, v68
	v_fmac_f32_e32 v7, v164, v100
	s_waitcnt vmcnt(6)
	v_fmac_f32_e32 v10, v165, v37
	v_fmac_f32_e32 v11, v165, v69
	v_fmac_f32_e32 v7, v165, v101
	s_waitcnt vmcnt(5)
	v_fmac_f32_e32 v10, v166, v38
	v_fmac_f32_e32 v11, v166, v70
	v_fmac_f32_e32 v7, v166, v102
	s_waitcnt vmcnt(4)
	v_fmac_f32_e32 v10, v167, v39
	v_fmac_f32_e32 v11, v167, v71
	v_fmac_f32_e32 v7, v167, v103
	s_waitcnt vmcnt(3)
	v_fmac_f32_e32 v10, v168, v40
	v_fmac_f32_e32 v11, v168, v72
	v_fmac_f32_e32 v7, v168, v104
	s_waitcnt vmcnt(2)
	v_fmac_f32_e32 v10, v169, v41
	v_fmac_f32_e32 v11, v169, v73
	v_fmac_f32_e32 v7, v169, v105
	s_waitcnt vmcnt(1)
	v_fmac_f32_e32 v10, v170, v42
	v_fmac_f32_e32 v11, v170, v74
	v_fmac_f32_e32 v7, v170, v106
	s_waitcnt vmcnt(0)
	v_fmac_f32_e32 v10, v171, v43
	v_fmac_f32_e32 v11, v171, v75
	v_fmac_f32_e32 v7, v171, v107
	ds_write2st64_b32 v1, v10, v11 offset0:96 offset1:97
	ds_write_b32 v1, v7 offset:25088
	s_waitcnt lgkmcnt(0)
	s_barrier
	s_and_saveexec_b64 s[4:5], vcc
	s_cbranch_execz .LBB0_22
	s_load_dwordx2 s[18:19], s[8:9], 0x80
	s_ashr_i32 s17, s16, 31
	s_mul_i32 s56, s14, 0xc000
	s_mul_hi_i32 s15, s14, 0xc000
	v_mov_b64_e32 v[18:19], s[12:13]
	s_waitcnt lgkmcnt(0)
	s_add_u32 s18, s18, s56
	s_addc_u32 s15, s19, s15
	s_lshl_b64 s[16:17], s[16:17], 2
	s_add_u32 s18, s18, s16
	s_addc_u32 s19, s15, s17
	global_load_dword v7, v2, s[18:19]
	ds_read2st64_b32 v[8:9], v5 offset0:96 offset1:99
	ds_read2st64_b32 v[10:11], v5 offset0:102 offset1:105
	ds_read2st64_b32 v[12:13], v5 offset0:108 offset1:111
	ds_read2st64_b32 v[14:15], v5 offset0:114 offset1:117
	v_mad_u64_u32 v[16:17], s[14:15], s14, 3, v[0:1]
	v_mad_i64_i32 v[16:17], s[14:15], v16, s23, v[18:19]
	v_lshl_add_u64 v[16:17], v[16:17], 0, s[16:17]
	s_waitcnt vmcnt(0) lgkmcnt(3)
	v_add_f32_e32 v7, v7, v8
	v_add_f32_e32 v7, v7, v9
	s_waitcnt lgkmcnt(2)
	v_add_f32_e32 v7, v7, v10
	v_add_f32_e32 v7, v7, v11
	s_waitcnt lgkmcnt(1)
	v_add_f32_e32 v7, v7, v12
	v_add_f32_e32 v7, v7, v13
	s_waitcnt lgkmcnt(0)
	v_add_f32_e32 v7, v7, v14
	v_add_f32_e32 v7, v7, v15
	v_lshl_add_u64 v[8:9], v[16:17], 0, v[2:3]
	global_store_dword v[8:9], v7, off
	s_branch .LBB0_22

.LBB0_59:
	s_lshr_b32 s48, s10, 6
	s_waitcnt lgkmcnt(0)
	v_cvt_f32_u32_e32 v0, s48
	s_sub_i32 s56, 0, s48
	s_abs_i32 s55, s49
	s_and_b64 s[46:47], s[28:29], s[46:47]
	v_rcp_iflag_f32_e32 v0, v0
	s_ashr_i32 s54, s49, 31
	s_load_dwordx2 s[4:5], s[4:5], 0x0
	v_mul_f32_e32 v0, 0x4f7ffffe, v0
	v_cvt_u32_f32_e32 v0, v0
	s_nop 0
	v_readfirstlane_b32 s57, v0
	s_mul_i32 s56, s56, s57
	s_mul_hi_u32 s56, s57, s56
	s_add_i32 s57, s57, s56
	s_mul_hi_u32 s56, s55, s57
	s_mul_i32 s57, s56, s48
	s_sub_i32 s55, s55, s57
	s_add_i32 s58, s56, 1
	s_sub_i32 s57, s55, s48
	s_cmp_ge_u32 s55, s48
	s_cselect_b32 s56, s58, s56
	s_cselect_b32 s55, s57, s55
	s_add_i32 s57, s56, 1
	s_cmp_ge_u32 s55, s48
	s_cselect_b32 s55, s57, s56
	s_xor_b32 s55, s55, s54
	s_sub_i32 s54, s55, s54
	s_mul_i32 s55, s54, s48
	s_lshl_b32 s48, s54, 6
	s_sub_i32 s54, s49, s55
	s_ashr_i32 s49, s48, 31
	s_lshl_b32 s54, s54, 6
	s_mul_i32 s55, s49, s10
	s_mul_hi_u32 s56, s48, s10
	v_or_b32_e32 v0, s54, v6
	s_add_i32 s57, s56, s55
	s_mul_i32 s56, s48, s10
	s_lshl_b64 s[56:57], s[56:57], 2
	v_cmp_gt_i32_e32 vcc, s10, v0
	s_waitcnt lgkmcnt(0)
	s_add_u32 s4, s4, s56
	s_addc_u32 s5, s5, s57
	v_cndmask_b32_e32 v0, 0, v0, vcc
	v_ashrrev_i32_e32 v1, 31, v0
	v_lshl_add_u64 v[0:1], v[0:1], 2, s[4:5]
	s_lshl_b32 s4, s10, 1
	s_mov_b32 s5, s11
	v_lshl_add_u64 v[10:11], s[4:5], 2, v[0:1]
	s_mul_i32 s4, s10, 3
	v_lshl_add_u64 v[22:23], s[4:5], 2, v[0:1]
	s_lshl_b32 s4, s10, 2
	v_lshl_add_u64 v[24:25], s[4:5], 2, v[0:1]
	s_mul_i32 s4, s10, 5
	v_lshl_add_u64 v[26:27], s[4:5], 2, v[0:1]
	s_mul_i32 s4, s10, 6
	v_lshl_add_u64 v[28:29], s[4:5], 2, v[0:1]
	s_mul_i32 s4, s10, 7
	v_lshl_add_u64 v[2:3], s[10:11], 2, v[0:1]
	v_lshl_add_u64 v[30:31], s[4:5], 2, v[0:1]
	s_lshl_b32 s4, s10, 3
	global_load_dword v34, v[0:1], off nt
	global_load_dword v35, v[2:3], off nt
	global_load_dword v36, v[10:11], off nt
	global_load_dword v37, v[22:23], off nt
	global_load_dword v38, v[24:25], off nt
	global_load_dword v39, v[26:27], off nt
	global_load_dword v40, v[28:29], off nt
	global_load_dword v41, v[30:31], off nt
	v_lshl_add_u64 v[2:3], s[4:5], 2, v[0:1]
	s_mul_i32 s4, s10, 9
	v_lshl_add_u64 v[10:11], s[4:5], 2, v[0:1]
	s_mul_i32 s4, s10, 10
	v_lshl_add_u64 v[22:23], s[4:5], 2, v[0:1]
	s_mul_i32 s4, s10, 11
	v_lshl_add_u64 v[24:25], s[4:5], 2, v[0:1]
	s_mul_i32 s4, s10, 12
	v_lshl_add_u64 v[26:27], s[4:5], 2, v[0:1]
	s_mul_i32 s4, s10, 13
	v_lshl_add_u64 v[28:29], s[4:5], 2, v[0:1]
	s_mul_i32 s4, s10, 14
	v_lshl_add_u64 v[30:31], s[4:5], 2, v[0:1]
	s_mul_i32 s4, s10, 15
	v_lshl_add_u64 v[32:33], s[4:5], 2, v[0:1]
	s_lshl_b32 s4, s10, 4
	global_load_dword v42, v[2:3], off nt
	global_load_dword v43, v[10:11], off nt
	global_load_dword v44, v[22:23], off nt
	global_load_dword v45, v[24:25], off nt
	global_load_dword v46, v[26:27], off nt
	global_load_dword v47, v[28:29], off nt
	global_load_dword v48, v[30:31], off nt
	global_load_dword v49, v[32:33], off nt
	v_lshl_add_u64 v[2:3], s[4:5], 2, v[0:1]
	s_mul_i32 s4, s10, 17
	v_lshl_add_u64 v[10:11], s[4:5], 2, v[0:1]
	s_mul_i32 s4, s10, 18
	v_lshl_add_u64 v[22:23], s[4:5], 2, v[0:1]
	s_mul_i32 s4, s10, 19
	v_lshl_add_u64 v[24:25], s[4:5], 2, v[0:1]
	s_mul_i32 s4, s10, 20
	v_lshl_add_u64 v[26:27], s[4:5], 2, v[0:1]
	s_mul_i32 s4, s10, 21
	v_lshl_add_u64 v[28:29], s[4:5], 2, v[0:1]
	s_mul_i32 s4, s10, 22
	v_lshl_add_u64 v[30:31], s[4:5], 2, v[0:1]
	s_mul_i32 s4, s10, 23
	v_lshl_add_u64 v[32:33], s[4:5], 2, v[0:1]
	s_mul_i32 s4, s10, 24
	global_load_dword v50, v[2:3], off nt
	global_load_dword v51, v[10:11], off nt
	global_load_dword v52, v[22:23], off nt
	global_load_dword v53, v[24:25], off nt
	global_load_dword v54, v[26:27], off nt
	global_load_dword v55, v[28:29], off nt
	global_load_dword v56, v[30:31], off nt
	global_load_dword v57, v[32:33], off nt
	v_lshl_add_u64 v[2:3], s[4:5], 2, v[0:1]
	s_mul_i32 s4, s10, 25
	v_lshl_add_u64 v[10:11], s[4:5], 2, v[0:1]
	s_mul_i32 s4, s10, 26
	v_lshl_add_u64 v[22:23], s[4:5], 2, v[0:1]
	s_mul_i32 s4, s10, 27
	v_lshl_add_u64 v[24:25], s[4:5], 2, v[0:1]
	s_mul_i32 s4, s10, 28
	v_lshl_add_u64 v[26:27], s[4:5], 2, v[0:1]
	s_mul_i32 s4, s10, 29
	v_lshl_add_u64 v[28:29], s[4:5], 2, v[0:1]
	s_mul_i32 s4, s10, 30
	v_lshl_add_u64 v[30:31], s[4:5], 2, v[0:1]
	s_mul_i32 s4, s10, 31
	v_lshl_add_u64 v[32:33], s[4:5], 2, v[0:1]
	s_lshl_b32 s4, s10, 5
	global_load_dword v58, v[2:3], off nt
	global_load_dword v59, v[10:11], off nt
	global_load_dword v60, v[22:23], off nt
	global_load_dword v61, v[24:25], off nt
	global_load_dword v62, v[26:27], off nt
	global_load_dword v63, v[28:29], off nt
	global_load_dword v64, v[30:31], off nt
	global_load_dword v65, v[32:33], off nt
	v_lshl_add_u64 v[2:3], s[4:5], 2, v[0:1]
	s_mul_i32 s4, s10, 33
	v_lshl_add_u64 v[10:11], s[4:5], 2, v[0:1]
	s_mul_i32 s4, s10, 34
	v_lshl_add_u64 v[22:23], s[4:5], 2, v[0:1]
	s_mul_i32 s4, s10, 35
	v_lshl_add_u64 v[24:25], s[4:5], 2, v[0:1]
	s_mul_i32 s4, s10, 36
	v_lshl_add_u64 v[26:27], s[4:5], 2, v[0:1]
	s_mul_i32 s4, s10, 37
	v_lshl_add_u64 v[28:29], s[4:5], 2, v[0:1]
	s_mul_i32 s4, s10, 38
	v_lshl_add_u64 v[30:31], s[4:5], 2, v[0:1]
	s_mul_i32 s4, s10, 39
	v_lshl_add_u64 v[32:33], s[4:5], 2, v[0:1]
	s_mul_i32 s4, s10, 40
	global_load_dword v66, v[2:3], off nt
	global_load_dword v67, v[10:11], off nt
	global_load_dword v68, v[22:23], off nt
	global_load_dword v69, v[24:25], off nt
	global_load_dword v70, v[26:27], off nt
	global_load_dword v71, v[28:29], off nt
	global_load_dword v72, v[30:31], off nt
	global_load_dword v73, v[32:33], off nt
	v_lshl_add_u64 v[2:3], s[4:5], 2, v[0:1]
	s_mul_i32 s4, s10, 41
	v_lshl_add_u64 v[10:11], s[4:5], 2, v[0:1]
	s_mul_i32 s4, s10, 42
	v_lshl_add_u64 v[22:23], s[4:5], 2, v[0:1]
	s_mul_i32 s4, s10, 43
	v_lshl_add_u64 v[24:25], s[4:5], 2, v[0:1]
	s_mul_i32 s4, s10, 44
	v_lshl_add_u64 v[26:27], s[4:5], 2, v[0:1]
	s_mul_i32 s4, s10, 45
	v_lshl_add_u64 v[28:29], s[4:5], 2, v[0:1]
	s_mul_i32 s4, s10, 46
	v_lshl_add_u64 v[30:31], s[4:5], 2, v[0:1]
	s_mul_i32 s4, s10, 47
	v_lshl_add_u64 v[32:33], s[4:5], 2, v[0:1]
	s_mul_i32 s4, s10, 48
	global_load_dword v74, v[2:3], off nt
	global_load_dword v75, v[10:11], off nt
	global_load_dword v76, v[22:23], off nt
	global_load_dword v77, v[24:25], off nt
	global_load_dword v78, v[26:27], off nt
	global_load_dword v79, v[28:29], off nt
	global_load_dword v80, v[30:31], off nt
	global_load_dword v81, v[32:33], off nt
	v_lshl_add_u64 v[2:3], s[4:5], 2, v[0:1]
	s_mul_i32 s4, s10, 49
	v_lshl_add_u64 v[10:11], s[4:5], 2, v[0:1]
	s_mul_i32 s4, s10, 50
	v_lshl_add_u64 v[22:23], s[4:5], 2, v[0:1]
	s_mul_i32 s4, s10, 51
	v_lshl_add_u64 v[24:25], s[4:5], 2, v[0:1]
	s_mul_i32 s4, s10, 52
	v_lshl_add_u64 v[26:27], s[4:5], 2, v[0:1]
	s_mul_i32 s4, s10, 53
	v_lshl_add_u64 v[28:29], s[4:5], 2, v[0:1]
	s_mul_i32 s4, s10, 54
	v_lshl_add_u64 v[30:31], s[4:5], 2, v[0:1]
	s_mul_i32 s4, s10, 55
	v_lshl_add_u64 v[32:33], s[4:5], 2, v[0:1]
	s_mul_i32 s4, s10, 56
	global_load_dword v82, v[2:3], off nt
	global_load_dword v83, v[10:11], off nt
	global_load_dword v84, v[22:23], off nt
	global_load_dword v85, v[24:25], off nt
	global_load_dword v86, v[26:27], off nt
	global_load_dword v87, v[28:29], off nt
	global_load_dword v88, v[30:31], off nt
	s_nop 0
	global_load_dword v32, v[32:33], off nt
	v_lshl_add_u64 v[2:3], s[4:5], 2, v[0:1]
	s_mul_i32 s4, s10, 57
	v_lshl_add_u64 v[10:11], s[4:5], 2, v[0:1]
	s_mul_i32 s4, s10, 58
	v_lshl_add_u64 v[22:23], s[4:5], 2, v[0:1]
	s_mul_i32 s4, s10, 59
	v_lshl_add_u64 v[24:25], s[4:5], 2, v[0:1]
	s_mul_i32 s4, s10, 60
	v_lshl_add_u64 v[26:27], s[4:5], 2, v[0:1]
	s_mul_i32 s4, s10, 61
	v_lshl_add_u64 v[28:29], s[4:5], 2, v[0:1]
	s_mul_i32 s4, s10, 62
	v_lshl_add_u64 v[30:31], s[4:5], 2, v[0:1]
	s_mul_i32 s4, s10, 63
	v_lshl_add_u64 v[0:1], s[4:5], 2, v[0:1]
	global_load_dword v33, v[2:3], off nt
	s_nop 0
	global_load_dword v10, v[10:11], off nt
	s_nop 0
	global_load_dword v11, v[22:23], off nt
	s_nop 0
	global_load_dword v22, v[24:25], off nt
	global_load_dword v23, v[26:27], off nt
	s_nop 0
	global_load_dword v24, v[28:29], off nt
	global_load_dword v25, v[30:31], off nt
	global_load_dword v26, v[0:1], off nt
	s_waitcnt vmcnt(62)
	v_cvt_pk_bf16_f32 v0, v34, v35
	s_waitcnt vmcnt(60)
	v_cvt_pk_bf16_f32 v1, v36, v37
	s_waitcnt vmcnt(58)
	v_cvt_pk_bf16_f32 v2, v38, v39
	s_waitcnt vmcnt(56)
	v_cvt_pk_bf16_f32 v3, v40, v41
	ds_write_b128 v18, v[0:3]
	s_waitcnt vmcnt(54)
	v_cvt_pk_bf16_f32 v0, v42, v43
	s_waitcnt vmcnt(52)
	v_cvt_pk_bf16_f32 v1, v44, v45
	s_waitcnt vmcnt(50)
	v_cvt_pk_bf16_f32 v2, v46, v47
	s_waitcnt vmcnt(48)
	v_cvt_pk_bf16_f32 v3, v48, v49
	ds_write_b128 v18, v[0:3] offset:16
	s_waitcnt vmcnt(46)
	v_cvt_pk_bf16_f32 v0, v50, v51
	s_waitcnt vmcnt(44)
	v_cvt_pk_bf16_f32 v1, v52, v53
	s_waitcnt vmcnt(42)
	v_cvt_pk_bf16_f32 v2, v54, v55
	s_waitcnt vmcnt(40)
	v_cvt_pk_bf16_f32 v3, v56, v57
	ds_write_b128 v18, v[0:3] offset:32
	s_waitcnt vmcnt(38)
	v_cvt_pk_bf16_f32 v0, v58, v59
	s_waitcnt vmcnt(36)
	v_cvt_pk_bf16_f32 v1, v60, v61
	s_waitcnt vmcnt(34)
	v_cvt_pk_bf16_f32 v2, v62, v63
	s_waitcnt vmcnt(32)
	v_cvt_pk_bf16_f32 v3, v64, v65
	ds_write_b128 v18, v[0:3] offset:48
	s_andn2_b64 vcc, exec, s[46:47]
	s_waitcnt vmcnt(30)
	v_cvt_pk_bf16_f32 v0, v66, v67
	s_waitcnt vmcnt(28)
	v_cvt_pk_bf16_f32 v1, v68, v69
	s_waitcnt vmcnt(26)
	v_cvt_pk_bf16_f32 v2, v70, v71
	s_waitcnt vmcnt(24)
	v_cvt_pk_bf16_f32 v3, v72, v73
	ds_write_b128 v18, v[0:3] offset:64
	s_waitcnt vmcnt(22)
	v_cvt_pk_bf16_f32 v0, v74, v75
	s_waitcnt vmcnt(20)
	v_cvt_pk_bf16_f32 v1, v76, v77
	s_waitcnt vmcnt(18)
	v_cvt_pk_bf16_f32 v2, v78, v79
	s_waitcnt vmcnt(16)
	v_cvt_pk_bf16_f32 v3, v80, v81
	ds_write_b128 v18, v[0:3] offset:80
	s_waitcnt vmcnt(14)
	v_cvt_pk_bf16_f32 v0, v82, v83
	s_waitcnt vmcnt(12)
	v_cvt_pk_bf16_f32 v1, v84, v85
	s_waitcnt vmcnt(10)
	v_cvt_pk_bf16_f32 v2, v86, v87
	s_waitcnt vmcnt(8)
	v_cvt_pk_bf16_f32 v3, v88, v32
	ds_write_b128 v18, v[0:3] offset:96
	s_waitcnt vmcnt(6)
	v_cvt_pk_bf16_f32 v0, v33, v10
	v_cndmask_b32_e64 v10, 0, 1, s[46:47]
	s_waitcnt vmcnt(4)
	v_cvt_pk_bf16_f32 v1, v11, v22
	v_or_b32_e32 v22, s54, v5
	s_waitcnt vmcnt(2)
	v_cvt_pk_bf16_f32 v2, v23, v24
	v_cmp_ne_u32_e64 s[4:5], 1, v10
	s_waitcnt vmcnt(0)
	v_cvt_pk_bf16_f32 v3, v25, v26
	ds_write_b128 v18, v[0:3] offset:112
	ds_read_b128 v[0:3], v19
	v_mov_b32_e32 v23, v22
	s_cbranch_vccnz .LBB0_61
	v_cmp_lt_i32_e32 vcc, s50, v22
	v_and_b32_e32 v23, 0x47, v22
	s_nop 0
	v_cndmask_b32_e32 v10, 0, v20, vcc
	v_add_lshl_u32 v10, v10, v22, 1
	v_and_b32_e32 v10, 0xffffff00, v10
	v_cndmask_b32_e32 v11, 0, v21, vcc
	v_or3_b32 v23, v11, v23, v10

.LBB0_523:
	s_load_dwordx2 s[60:61], s[60:61], 0x0
	s_waitcnt lgkmcnt(0)
	s_add_u32 vcc_lo, s60, s96
	s_addc_u32 vcc_hi, s61, s97
	s_add_i32 s7, s46, 63
	s_lshr_b32 s7, s7, 6
	v_cvt_f32_u32_e32 v2, s7
	s_sub_i32 s96, 0, s7
	s_abs_i32 s61, s82
	s_ashr_i32 s60, s82, 31
	v_rcp_iflag_f32_e32 v2, v2
	s_nop 0
	v_mul_f32_e32 v2, 0x4f7ffffe, v2
	v_cvt_u32_f32_e32 v2, v2
	s_nop 0
	v_readfirstlane_b32 s97, v2
	s_mul_i32 s96, s96, s97
	s_mul_hi_u32 s96, s97, s96
	s_add_i32 s97, s97, s96
	s_mul_hi_u32 s96, s61, s97
	s_mul_i32 s97, s96, s7
	s_sub_i32 s61, s61, s97
	s_add_i32 s17, s96, 1
	s_sub_i32 s97, s61, s7
	s_cmp_ge_u32 s61, s7
	s_cselect_b32 s17, s17, s96
	s_cselect_b32 s61, s97, s61
	s_add_i32 s96, s17, 1
	s_cmp_ge_u32 s61, s7
	s_cselect_b32 s17, s96, s17
	s_xor_b32 s17, s17, s60
	s_sub_i32 s17, s17, s60
	s_lshl_b32 s96, s17, 6
	s_ashr_i32 s97, s96, 31
	s_mul_i32 s7, s17, s7
	s_mul_hi_u32 s17, s96, s46
	s_mul_i32 s61, s97, s46
	s_sub_i32 s7, s82, s7
	s_mul_i32 s60, s96, s46
	s_add_i32 s61, s17, s61
	s_lshl_b32 s7, s7, 6
	s_lshl_b64 s[60:61], s[60:61], 2
	v_or_b32_e32 v2, s7, v170
	s_add_u32 s60, vcc_lo, s60
	s_addc_u32 s61, vcc_hi, s61
	v_cmp_gt_i32_e32 vcc, s46, v2
	s_or_b64 s[74:75], s[10:11], s[74:75]
	s_nop 0
	v_cndmask_b32_e32 v2, 0, v2, vcc
	v_ashrrev_i32_e32 v3, 31, v2
	v_lshl_add_u64 v[2:3], v[2:3], 2, s[60:61]
	s_lshl_b32 s60, s46, 1
	s_mov_b32 s61, s47
	v_lshl_add_u64 v[10:11], s[60:61], 2, v[2:3]
	s_mul_i32 s60, s46, 3
	v_lshl_add_u64 v[12:13], s[60:61], 2, v[2:3]
	s_lshl_b32 s60, s46, 2
	v_lshl_add_u64 v[24:25], s[60:61], 2, v[2:3]
	s_mul_i32 s60, s46, 5
	v_lshl_add_u64 v[26:27], s[60:61], 2, v[2:3]
	s_mul_i32 s60, s46, 6
	v_lshl_add_u64 v[28:29], s[60:61], 2, v[2:3]
	s_mul_i32 s60, s46, 7
	v_lshl_add_u64 v[4:5], s[46:47], 2, v[2:3]
	v_lshl_add_u64 v[30:31], s[60:61], 2, v[2:3]
	s_lshl_b32 s60, s46, 3
	global_load_dword v34, v[2:3], off nt
	global_load_dword v35, v[4:5], off nt
	global_load_dword v36, v[10:11], off nt
	global_load_dword v37, v[12:13], off nt
	global_load_dword v38, v[24:25], off nt
	global_load_dword v39, v[26:27], off nt
	global_load_dword v40, v[28:29], off nt
	global_load_dword v41, v[30:31], off nt
	v_lshl_add_u64 v[4:5], s[60:61], 2, v[2:3]
	s_mul_i32 s60, s46, 9
	v_lshl_add_u64 v[10:11], s[60:61], 2, v[2:3]
	s_mul_i32 s60, s46, 10
	v_lshl_add_u64 v[12:13], s[60:61], 2, v[2:3]
	s_mul_i32 s60, s46, 11
	v_lshl_add_u64 v[24:25], s[60:61], 2, v[2:3]
	s_mul_i32 s60, s46, 12
	v_lshl_add_u64 v[26:27], s[60:61], 2, v[2:3]
	s_mul_i32 s60, s46, 13
	v_lshl_add_u64 v[28:29], s[60:61], 2, v[2:3]
	s_mul_i32 s60, s46, 14
	v_lshl_add_u64 v[30:31], s[60:61], 2, v[2:3]
	s_mul_i32 s60, s46, 15
	v_lshl_add_u64 v[32:33], s[60:61], 2, v[2:3]
	s_lshl_b32 s60, s46, 4
	global_load_dword v42, v[4:5], off nt
	global_load_dword v43, v[10:11], off nt
	global_load_dword v44, v[12:13], off nt
	global_load_dword v45, v[24:25], off nt
	global_load_dword v46, v[26:27], off nt
	global_load_dword v47, v[28:29], off nt
	global_load_dword v48, v[30:31], off nt
	global_load_dword v49, v[32:33], off nt
	v_lshl_add_u64 v[4:5], s[60:61], 2, v[2:3]
	s_mul_i32 s60, s46, 17
	v_lshl_add_u64 v[10:11], s[60:61], 2, v[2:3]
	s_mul_i32 s60, s46, 18
	v_lshl_add_u64 v[12:13], s[60:61], 2, v[2:3]
	s_mul_i32 s60, s46, 19
	v_lshl_add_u64 v[24:25], s[60:61], 2, v[2:3]
	s_mul_i32 s60, s46, 20
	v_lshl_add_u64 v[26:27], s[60:61], 2, v[2:3]
	s_mul_i32 s60, s46, 21
	v_lshl_add_u64 v[28:29], s[60:61], 2, v[2:3]
	s_mul_i32 s60, s46, 22
	v_lshl_add_u64 v[30:31], s[60:61], 2, v[2:3]
	s_mul_i32 s60, s46, 23
	v_lshl_add_u64 v[32:33], s[60:61], 2, v[2:3]
	s_mul_i32 s60, s46, 24
	global_load_dword v50, v[4:5], off nt
	global_load_dword v51, v[10:11], off nt
	global_load_dword v52, v[12:13], off nt
	global_load_dword v53, v[24:25], off nt
	global_load_dword v54, v[26:27], off nt
	global_load_dword v55, v[28:29], off nt
	global_load_dword v56, v[30:31], off nt
	global_load_dword v57, v[32:33], off nt
	v_lshl_add_u64 v[4:5], s[60:61], 2, v[2:3]
	s_mul_i32 s60, s46, 25
	v_lshl_add_u64 v[10:11], s[60:61], 2, v[2:3]
	s_mul_i32 s60, s46, 26
	v_lshl_add_u64 v[12:13], s[60:61], 2, v[2:3]
	s_mul_i32 s60, s46, 27
	v_lshl_add_u64 v[24:25], s[60:61], 2, v[2:3]
	s_mul_i32 s60, s46, 28
	v_lshl_add_u64 v[26:27], s[60:61], 2, v[2:3]
	s_mul_i32 s60, s46, 29
	v_lshl_add_u64 v[28:29], s[60:61], 2, v[2:3]
	s_mul_i32 s60, s46, 30
	v_lshl_add_u64 v[30:31], s[60:61], 2, v[2:3]
	s_mul_i32 s60, s46, 31
	v_lshl_add_u64 v[32:33], s[60:61], 2, v[2:3]
	s_lshl_b32 s60, s46, 5
	global_load_dword v58, v[4:5], off nt
	global_load_dword v59, v[10:11], off nt
	global_load_dword v60, v[12:13], off nt
	global_load_dword v61, v[24:25], off nt
	global_load_dword v62, v[26:27], off nt
	global_load_dword v63, v[28:29], off nt
	global_load_dword v64, v[30:31], off nt
	global_load_dword v65, v[32:33], off nt
	v_lshl_add_u64 v[4:5], s[60:61], 2, v[2:3]
	s_mul_i32 s60, s46, 33
	v_lshl_add_u64 v[10:11], s[60:61], 2, v[2:3]
	s_mul_i32 s60, s46, 34
	v_lshl_add_u64 v[12:13], s[60:61], 2, v[2:3]
	s_mul_i32 s60, s46, 35
	v_lshl_add_u64 v[24:25], s[60:61], 2, v[2:3]
	s_mul_i32 s60, s46, 36
	v_lshl_add_u64 v[26:27], s[60:61], 2, v[2:3]
	s_mul_i32 s60, s46, 37
	v_lshl_add_u64 v[28:29], s[60:61], 2, v[2:3]
	s_mul_i32 s60, s46, 38
	v_lshl_add_u64 v[30:31], s[60:61], 2, v[2:3]
	s_mul_i32 s60, s46, 39
	v_lshl_add_u64 v[32:33], s[60:61], 2, v[2:3]
	s_mul_i32 s60, s46, 40
	global_load_dword v66, v[4:5], off nt
	global_load_dword v67, v[10:11], off nt
	global_load_dword v68, v[12:13], off nt
	global_load_dword v69, v[24:25], off nt
	global_load_dword v70, v[26:27], off nt
	global_load_dword v71, v[28:29], off nt
	global_load_dword v72, v[30:31], off nt
	global_load_dword v73, v[32:33], off nt
	v_lshl_add_u64 v[4:5], s[60:61], 2, v[2:3]
	s_mul_i32 s60, s46, 41
	v_lshl_add_u64 v[10:11], s[60:61], 2, v[2:3]
	s_mul_i32 s60, s46, 42
	v_lshl_add_u64 v[12:13], s[60:61], 2, v[2:3]
	s_mul_i32 s60, s46, 43
	v_lshl_add_u64 v[24:25], s[60:61], 2, v[2:3]
	s_mul_i32 s60, s46, 44
	v_lshl_add_u64 v[26:27], s[60:61], 2, v[2:3]
	s_mul_i32 s60, s46, 45
	v_lshl_add_u64 v[28:29], s[60:61], 2, v[2:3]
	s_mul_i32 s60, s46, 46
	v_lshl_add_u64 v[30:31], s[60:61], 2, v[2:3]
	s_mul_i32 s60, s46, 47
	v_lshl_add_u64 v[32:33], s[60:61], 2, v[2:3]
	s_mul_i32 s60, s46, 48
	global_load_dword v74, v[4:5], off nt
	global_load_dword v75, v[10:11], off nt
	global_load_dword v76, v[12:13], off nt
	global_load_dword v77, v[24:25], off nt
	global_load_dword v78, v[26:27], off nt
	global_load_dword v79, v[28:29], off nt
	global_load_dword v80, v[30:31], off nt
	global_load_dword v81, v[32:33], off nt
	v_lshl_add_u64 v[4:5], s[60:61], 2, v[2:3]
	s_mul_i32 s60, s46, 49
	v_lshl_add_u64 v[10:11], s[60:61], 2, v[2:3]
	s_mul_i32 s60, s46, 50
	v_lshl_add_u64 v[12:13], s[60:61], 2, v[2:3]
	s_mul_i32 s60, s46, 51
	v_lshl_add_u64 v[24:25], s[60:61], 2, v[2:3]
	s_mul_i32 s60, s46, 52
	v_lshl_add_u64 v[26:27], s[60:61], 2, v[2:3]
	s_mul_i32 s60, s46, 53
	v_lshl_add_u64 v[28:29], s[60:61], 2, v[2:3]
	s_mul_i32 s60, s46, 54
	v_lshl_add_u64 v[30:31], s[60:61], 2, v[2:3]
	s_mul_i32 s60, s46, 55
	v_lshl_add_u64 v[32:33], s[60:61], 2, v[2:3]
	s_mul_i32 s60, s46, 56
	global_load_dword v82, v[4:5], off nt
	global_load_dword v83, v[10:11], off nt
	global_load_dword v84, v[12:13], off nt
	global_load_dword v85, v[24:25], off nt
	global_load_dword v86, v[26:27], off nt
	global_load_dword v87, v[28:29], off nt
	global_load_dword v88, v[30:31], off nt
	s_nop 0
	global_load_dword v32, v[32:33], off nt
	v_lshl_add_u64 v[4:5], s[60:61], 2, v[2:3]
	s_mul_i32 s60, s46, 57
	v_lshl_add_u64 v[10:11], s[60:61], 2, v[2:3]
	s_mul_i32 s60, s46, 58
	v_lshl_add_u64 v[12:13], s[60:61], 2, v[2:3]
	s_mul_i32 s60, s46, 59
	v_lshl_add_u64 v[24:25], s[60:61], 2, v[2:3]
	s_mul_i32 s60, s46, 60
	v_lshl_add_u64 v[26:27], s[60:61], 2, v[2:3]
	s_mul_i32 s60, s46, 61
	v_lshl_add_u64 v[28:29], s[60:61], 2, v[2:3]
	s_mul_i32 s60, s46, 62
	v_lshl_add_u64 v[30:31], s[60:61], 2, v[2:3]
	s_mul_i32 s60, s46, 63
	v_lshl_add_u64 v[2:3], s[60:61], 2, v[2:3]
	global_load_dword v33, v[4:5], off nt
	s_nop 0
	global_load_dword v10, v[10:11], off nt
	s_nop 0
	global_load_dword v11, v[12:13], off nt
	s_nop 0
	global_load_dword v12, v[24:25], off nt
	global_load_dword v13, v[26:27], off nt
	s_nop 0
	global_load_dword v24, v[28:29], off nt
	global_load_dword v25, v[30:31], off nt
	global_load_dword v26, v[2:3], off nt
	s_waitcnt vmcnt(0)
	v_cvt_pk_bf16_f32 v2, v34, v35
	v_cvt_pk_bf16_f32 v3, v36, v37
	v_cvt_pk_bf16_f32 v4, v38, v39
	v_cvt_pk_bf16_f32 v5, v40, v41
	ds_write_b128 v22, v[2:5]
	v_cvt_pk_bf16_f32 v2, v42, v43
	v_cvt_pk_bf16_f32 v3, v44, v45
	v_cvt_pk_bf16_f32 v4, v46, v47
	v_cvt_pk_bf16_f32 v5, v48, v49
	ds_write_b128 v22, v[2:5] offset:16
	v_cvt_pk_bf16_f32 v2, v50, v51
	v_cvt_pk_bf16_f32 v3, v52, v53
	v_cvt_pk_bf16_f32 v4, v54, v55
	v_cvt_pk_bf16_f32 v5, v56, v57
	ds_write_b128 v22, v[2:5] offset:32
	v_cvt_pk_bf16_f32 v2, v58, v59
	v_cvt_pk_bf16_f32 v3, v60, v61
	v_cvt_pk_bf16_f32 v4, v62, v63
	v_cvt_pk_bf16_f32 v5, v64, v65
	ds_write_b128 v22, v[2:5] offset:48
	s_and_b64 s[60:61], s[10:11], s[88:89]
	s_and_b64 s[74:75], s[74:75], exec
	s_cselect_b32 s17, 0, 2
	v_cvt_pk_bf16_f32 v2, v66, v67
	s_and_b64 s[60:61], s[60:61], exec
	v_cvt_pk_bf16_f32 v3, v68, v69
	s_cselect_b32 s74, 1, s17
	v_cvt_pk_bf16_f32 v4, v70, v71
	s_cmp_gt_i32 s74, 1
	v_cvt_pk_bf16_f32 v5, v72, v73
	ds_write_b128 v22, v[2:5] offset:64
	s_mov_b64 s[60:61], -1
	v_cvt_pk_bf16_f32 v2, v74, v75
	v_cvt_pk_bf16_f32 v3, v76, v77
	v_cvt_pk_bf16_f32 v4, v78, v79
	v_cvt_pk_bf16_f32 v5, v80, v81
	ds_write_b128 v22, v[2:5] offset:80
	v_cvt_pk_bf16_f32 v2, v82, v83
	v_cvt_pk_bf16_f32 v3, v84, v85
	v_cvt_pk_bf16_f32 v4, v86, v87
	v_cvt_pk_bf16_f32 v5, v88, v32
	ds_write_b128 v22, v[2:5] offset:96
	v_cvt_pk_bf16_f32 v2, v33, v10
	v_cvt_pk_bf16_f32 v3, v11, v12
	v_or_b32_e32 v12, s7, v14
	v_cvt_pk_bf16_f32 v4, v13, v24
	v_cvt_pk_bf16_f32 v5, v25, v26
	ds_write_b128 v22, v[2:5] offset:112
	ds_read_b128 v[2:5], v23
	s_cbranch_scc0 .LBB0_525
	v_cmp_gt_i32_e32 vcc, s93, v12
	s_mov_b64 s[60:61], 0
	s_nop 0
	v_cndmask_b32_e32 v10, v237, v238, vcc
	v_cmp_lt_i32_e32 vcc, s48, v12
	s_nop 1
	v_cndmask_b32_e32 v10, 0, v10, vcc
	v_add_u32_e32 v13, v10, v12

.LBB0_847:
	s_load_dwordx2 s[66:67], s[96:97], 0x0
	s_waitcnt lgkmcnt(0)
	s_add_u32 s59, s66, s88
	s_addc_u32 s65, s67, s89
	s_add_i32 s66, s46, 63
	s_lshr_b32 s66, s66, 6
	v_cvt_f32_u32_e32 v2, s66
	s_sub_i32 s79, 0, s66
	s_abs_i32 s78, s58
	s_ashr_i32 s67, s58, 31
	v_rcp_iflag_f32_e32 v2, v2
	s_nop 0
	v_mul_f32_e32 v2, 0x4f7ffffe, v2
	v_cvt_u32_f32_e32 v2, v2
	s_nop 0
	v_readfirstlane_b32 s80, v2
	s_mul_i32 s79, s79, s80
	s_mul_hi_u32 s79, s80, s79
	s_add_i32 s80, s80, s79
	s_mul_hi_u32 s79, s78, s80
	s_mul_i32 s80, s79, s66
	s_sub_i32 s78, s78, s80
	s_add_i32 s81, s79, 1
	s_sub_i32 s80, s78, s66
	s_cmp_ge_u32 s78, s66
	s_cselect_b32 s79, s81, s79
	s_cselect_b32 s78, s80, s78
	s_add_i32 s80, s79, 1
	s_cmp_ge_u32 s78, s66
	s_cselect_b32 s78, s80, s79
	s_xor_b32 s78, s78, s67
	s_sub_i32 s67, s78, s67
	s_mul_i32 s66, s67, s66
	s_lshl_b32 s88, s67, 6
	s_sub_i32 s58, s58, s66
	s_ashr_i32 s89, s88, 31
	s_mul_hi_u32 s67, s88, s46
	s_lshl_b32 s58, s58, 6
	s_mul_i32 s78, s89, s46
	s_mul_i32 s66, s88, s46
	v_or_b32_e32 v2, s58, v166
	s_add_i32 s67, s67, s78
	s_lshl_b64 s[66:67], s[66:67], 2
	v_cmp_gt_i32_e32 vcc, s46, v2
	s_add_u32 s66, s59, s66
	s_addc_u32 s67, s65, s67
	v_cndmask_b32_e32 v2, 0, v2, vcc
	v_ashrrev_i32_e32 v3, 31, v2
	v_lshl_add_u64 v[2:3], v[2:3], 2, s[66:67]
	s_lshl_b32 s66, s46, 1
	s_mov_b32 s67, s47
	v_lshl_add_u64 v[6:7], s[66:67], 2, v[2:3]
	s_mul_i32 s66, s46, 3
	v_lshl_add_u64 v[18:19], s[66:67], 2, v[2:3]
	s_lshl_b32 s66, s46, 2
	v_lshl_add_u64 v[20:21], s[66:67], 2, v[2:3]
	s_mul_i32 s66, s46, 5
	v_lshl_add_u64 v[22:23], s[66:67], 2, v[2:3]
	s_mul_i32 s66, s46, 6
	v_lshl_add_u64 v[24:25], s[66:67], 2, v[2:3]
	s_mul_i32 s66, s46, 7
	v_lshl_add_u64 v[4:5], s[46:47], 2, v[2:3]
	v_lshl_add_u64 v[26:27], s[66:67], 2, v[2:3]
	s_lshl_b32 s66, s46, 3
	global_load_dword v30, v[2:3], off nt
	global_load_dword v31, v[4:5], off nt
	global_load_dword v32, v[6:7], off nt
	global_load_dword v33, v[18:19], off nt
	global_load_dword v34, v[20:21], off nt
	global_load_dword v35, v[22:23], off nt
	global_load_dword v36, v[24:25], off nt
	global_load_dword v37, v[26:27], off nt
	v_lshl_add_u64 v[4:5], s[66:67], 2, v[2:3]
	s_mul_i32 s66, s46, 9
	v_lshl_add_u64 v[6:7], s[66:67], 2, v[2:3]
	s_mul_i32 s66, s46, 10
	v_lshl_add_u64 v[18:19], s[66:67], 2, v[2:3]
	s_mul_i32 s66, s46, 11
	v_lshl_add_u64 v[20:21], s[66:67], 2, v[2:3]
	s_mul_i32 s66, s46, 12
	v_lshl_add_u64 v[22:23], s[66:67], 2, v[2:3]
	s_mul_i32 s66, s46, 13
	v_lshl_add_u64 v[24:25], s[66:67], 2, v[2:3]
	s_mul_i32 s66, s46, 14
	v_lshl_add_u64 v[26:27], s[66:67], 2, v[2:3]
	s_mul_i32 s66, s46, 15
	v_lshl_add_u64 v[28:29], s[66:67], 2, v[2:3]
	s_lshl_b32 s66, s46, 4
	global_load_dword v38, v[4:5], off nt
	global_load_dword v39, v[6:7], off nt
	global_load_dword v40, v[18:19], off nt
	global_load_dword v41, v[20:21], off nt
	global_load_dword v42, v[22:23], off nt
	global_load_dword v43, v[24:25], off nt
	global_load_dword v44, v[26:27], off nt
	global_load_dword v45, v[28:29], off nt
	v_lshl_add_u64 v[4:5], s[66:67], 2, v[2:3]
	s_mul_i32 s66, s46, 17
	v_lshl_add_u64 v[6:7], s[66:67], 2, v[2:3]
	s_mul_i32 s66, s46, 18
	v_lshl_add_u64 v[18:19], s[66:67], 2, v[2:3]
	s_mul_i32 s66, s46, 19
	v_lshl_add_u64 v[20:21], s[66:67], 2, v[2:3]
	s_mul_i32 s66, s46, 20
	v_lshl_add_u64 v[22:23], s[66:67], 2, v[2:3]
	s_mul_i32 s66, s46, 21
	v_lshl_add_u64 v[24:25], s[66:67], 2, v[2:3]
	s_mul_i32 s66, s46, 22
	v_lshl_add_u64 v[26:27], s[66:67], 2, v[2:3]
	s_mul_i32 s66, s46, 23
	v_lshl_add_u64 v[28:29], s[66:67], 2, v[2:3]
	s_mul_i32 s66, s46, 24
	global_load_dword v46, v[4:5], off nt
	global_load_dword v47, v[6:7], off nt
	global_load_dword v48, v[18:19], off nt
	global_load_dword v49, v[20:21], off nt
	global_load_dword v50, v[22:23], off nt
	global_load_dword v51, v[24:25], off nt
	global_load_dword v52, v[26:27], off nt
	global_load_dword v53, v[28:29], off nt
	v_lshl_add_u64 v[4:5], s[66:67], 2, v[2:3]
	s_mul_i32 s66, s46, 25
	v_lshl_add_u64 v[6:7], s[66:67], 2, v[2:3]
	s_mul_i32 s66, s46, 26
	v_lshl_add_u64 v[18:19], s[66:67], 2, v[2:3]
	s_mul_i32 s66, s46, 27
	v_lshl_add_u64 v[20:21], s[66:67], 2, v[2:3]
	s_mul_i32 s66, s46, 28
	v_lshl_add_u64 v[22:23], s[66:67], 2, v[2:3]
	s_mul_i32 s66, s46, 29
	v_lshl_add_u64 v[24:25], s[66:67], 2, v[2:3]
	s_mul_i32 s66, s46, 30
	v_lshl_add_u64 v[26:27], s[66:67], 2, v[2:3]
	s_mul_i32 s66, s46, 31
	v_lshl_add_u64 v[28:29], s[66:67], 2, v[2:3]
	s_lshl_b32 s66, s46, 5
	global_load_dword v54, v[4:5], off nt
	global_load_dword v55, v[6:7], off nt
	global_load_dword v56, v[18:19], off nt
	global_load_dword v57, v[20:21], off nt
	global_load_dword v58, v[22:23], off nt
	global_load_dword v59, v[24:25], off nt
	global_load_dword v60, v[26:27], off nt
	global_load_dword v61, v[28:29], off nt
	v_lshl_add_u64 v[4:5], s[66:67], 2, v[2:3]
	s_mul_i32 s66, s46, 33
	v_lshl_add_u64 v[6:7], s[66:67], 2, v[2:3]
	s_mul_i32 s66, s46, 34
	v_lshl_add_u64 v[18:19], s[66:67], 2, v[2:3]
	s_mul_i32 s66, s46, 35
	v_lshl_add_u64 v[20:21], s[66:67], 2, v[2:3]
	s_mul_i32 s66, s46, 36
	v_lshl_add_u64 v[22:23], s[66:67], 2, v[2:3]
	s_mul_i32 s66, s46, 37
	v_lshl_add_u64 v[24:25], s[66:67], 2, v[2:3]
	s_mul_i32 s66, s46, 38
	v_lshl_add_u64 v[26:27], s[66:67], 2, v[2:3]
	s_mul_i32 s66, s46, 39
	v_lshl_add_u64 v[28:29], s[66:67], 2, v[2:3]
	s_mul_i32 s66, s46, 40
	global_load_dword v62, v[4:5], off nt
	global_load_dword v63, v[6:7], off nt
	global_load_dword v64, v[18:19], off nt
	global_load_dword v65, v[20:21], off nt
	global_load_dword v66, v[22:23], off nt
	global_load_dword v67, v[24:25], off nt
	global_load_dword v68, v[26:27], off nt
	global_load_dword v69, v[28:29], off nt
	v_lshl_add_u64 v[4:5], s[66:67], 2, v[2:3]
	s_mul_i32 s66, s46, 41
	v_lshl_add_u64 v[6:7], s[66:67], 2, v[2:3]
	s_mul_i32 s66, s46, 42
	v_lshl_add_u64 v[18:19], s[66:67], 2, v[2:3]
	s_mul_i32 s66, s46, 43
	v_lshl_add_u64 v[20:21], s[66:67], 2, v[2:3]
	s_mul_i32 s66, s46, 44
	v_lshl_add_u64 v[22:23], s[66:67], 2, v[2:3]
	s_mul_i32 s66, s46, 45
	v_lshl_add_u64 v[24:25], s[66:67], 2, v[2:3]
	s_mul_i32 s66, s46, 46
	v_lshl_add_u64 v[26:27], s[66:67], 2, v[2:3]
	s_mul_i32 s66, s46, 47
	v_lshl_add_u64 v[28:29], s[66:67], 2, v[2:3]
	s_mul_i32 s66, s46, 48
	global_load_dword v70, v[4:5], off nt
	global_load_dword v71, v[6:7], off nt
	global_load_dword v72, v[18:19], off nt
	global_load_dword v73, v[20:21], off nt
	global_load_dword v74, v[22:23], off nt
	global_load_dword v75, v[24:25], off nt
	global_load_dword v76, v[26:27], off nt
	global_load_dword v77, v[28:29], off nt
	v_lshl_add_u64 v[4:5], s[66:67], 2, v[2:3]
	s_mul_i32 s66, s46, 49
	v_lshl_add_u64 v[6:7], s[66:67], 2, v[2:3]
	s_mul_i32 s66, s46, 50
	v_lshl_add_u64 v[18:19], s[66:67], 2, v[2:3]
	s_mul_i32 s66, s46, 51
	v_lshl_add_u64 v[20:21], s[66:67], 2, v[2:3]
	s_mul_i32 s66, s46, 52
	v_lshl_add_u64 v[22:23], s[66:67], 2, v[2:3]
	s_mul_i32 s66, s46, 53
	v_lshl_add_u64 v[24:25], s[66:67], 2, v[2:3]
	s_mul_i32 s66, s46, 54
	v_lshl_add_u64 v[26:27], s[66:67], 2, v[2:3]
	s_mul_i32 s66, s46, 55
	v_lshl_add_u64 v[28:29], s[66:67], 2, v[2:3]
	s_mul_i32 s66, s46, 56
	global_load_dword v78, v[4:5], off nt
	global_load_dword v79, v[6:7], off nt
	global_load_dword v80, v[18:19], off nt
	global_load_dword v81, v[20:21], off nt
	global_load_dword v82, v[22:23], off nt
	global_load_dword v83, v[24:25], off nt
	global_load_dword v84, v[26:27], off nt
	s_nop 0
	global_load_dword v28, v[28:29], off nt
	v_lshl_add_u64 v[4:5], s[66:67], 2, v[2:3]
	s_mul_i32 s66, s46, 57
	v_lshl_add_u64 v[6:7], s[66:67], 2, v[2:3]
	s_mul_i32 s66, s46, 58
	v_lshl_add_u64 v[18:19], s[66:67], 2, v[2:3]
	s_mul_i32 s66, s46, 59
	v_lshl_add_u64 v[20:21], s[66:67], 2, v[2:3]
	s_mul_i32 s66, s46, 60
	v_lshl_add_u64 v[22:23], s[66:67], 2, v[2:3]
	s_mul_i32 s66, s46, 61
	v_lshl_add_u64 v[24:25], s[66:67], 2, v[2:3]
	s_mul_i32 s66, s46, 62
	v_lshl_add_u64 v[26:27], s[66:67], 2, v[2:3]
	s_mul_i32 s66, s46, 63
	v_lshl_add_u64 v[2:3], s[66:67], 2, v[2:3]
	global_load_dword v29, v[4:5], off nt
	s_nop 0
	global_load_dword v6, v[6:7], off nt
	s_nop 0
	global_load_dword v7, v[18:19], off nt
	s_nop 0
	global_load_dword v18, v[20:21], off nt
	global_load_dword v19, v[22:23], off nt
	s_nop 0
	global_load_dword v20, v[24:25], off nt
	global_load_dword v21, v[26:27], off nt
	global_load_dword v22, v[2:3], off nt
	s_waitcnt vmcnt(0)
	v_cvt_pk_bf16_f32 v2, v30, v31
	v_cvt_pk_bf16_f32 v3, v32, v33
	v_cvt_pk_bf16_f32 v4, v34, v35
	v_cvt_pk_bf16_f32 v5, v36, v37
	ds_write_b128 v16, v[2:5]
	v_cvt_pk_bf16_f32 v2, v38, v39
	v_cvt_pk_bf16_f32 v3, v40, v41
	v_cvt_pk_bf16_f32 v4, v42, v43
	v_cvt_pk_bf16_f32 v5, v44, v45
	ds_write_b128 v16, v[2:5] offset:16
	v_cvt_pk_bf16_f32 v2, v46, v47
	v_cvt_pk_bf16_f32 v3, v48, v49
	v_cvt_pk_bf16_f32 v4, v50, v51
	v_cvt_pk_bf16_f32 v5, v52, v53
	ds_write_b128 v16, v[2:5] offset:32
	v_cvt_pk_bf16_f32 v2, v54, v55
	v_cvt_pk_bf16_f32 v3, v56, v57
	v_cvt_pk_bf16_f32 v4, v58, v59
	v_cvt_pk_bf16_f32 v5, v60, v61
	ds_write_b128 v16, v[2:5] offset:48
	s_and_b64 s[66:67], s[8:9], s[74:75]
	s_or_b64 s[70:71], s[8:9], s[70:71]
	s_and_b64 s[70:71], s[70:71], exec
	v_cvt_pk_bf16_f32 v2, v62, v63
	s_cselect_b32 s59, 0, 2
	v_cvt_pk_bf16_f32 v3, v64, v65
	s_and_b64 s[66:67], s[66:67], exec
	v_cvt_pk_bf16_f32 v4, v66, v67
	s_cselect_b32 s59, 1, s59
	v_cvt_pk_bf16_f32 v5, v68, v69
	ds_write_b128 v16, v[2:5] offset:64
	s_cmp_gt_i32 s59, 1
	s_mov_b64 s[70:71], -1
	v_cvt_pk_bf16_f32 v2, v70, v71
	v_cvt_pk_bf16_f32 v3, v72, v73
	v_cvt_pk_bf16_f32 v4, v74, v75
	v_cvt_pk_bf16_f32 v5, v76, v77
	ds_write_b128 v16, v[2:5] offset:80
	v_cvt_pk_bf16_f32 v2, v78, v79
	v_cvt_pk_bf16_f32 v3, v80, v81
	v_cvt_pk_bf16_f32 v4, v82, v83
	v_cvt_pk_bf16_f32 v5, v84, v28
	ds_write_b128 v16, v[2:5] offset:96
	v_cvt_pk_bf16_f32 v2, v29, v6
	v_cvt_pk_bf16_f32 v3, v7, v18
	v_or_b32_e32 v18, s58, v8
	v_cvt_pk_bf16_f32 v4, v19, v20
	v_cvt_pk_bf16_f32 v5, v21, v22
	ds_write_b128 v16, v[2:5] offset:112
	ds_read_b128 v[2:5], v17
	s_cbranch_scc0 .LBB0_849
	v_cmp_gt_i32_e32 vcc, s93, v18
	s_mov_b64 s[70:71], 0
	s_nop 0
	v_cndmask_b32_e32 v6, v237, v238, vcc
	v_cmp_lt_i32_e32 vcc, s48, v18
	s_nop 1
	v_cndmask_b32_e32 v6, 0, v6, vcc
	v_add_u32_e32 v19, v6, v18
